# gate unit: row statistics with all loads up front and DPP/permlane reductions
# speedup vs baseline: 1.0023x; 1.0023x over previous
.LBB0_736:
	v_mov_b32_e32 v1, v194
	s_lshl_b32 s6, s69, 4
	v_readfirstlane_b32 s14, v1
	s_ashr_i32 s10, s14, 6
	s_add_i32 s8, s6, 0xe000
	s_lshl_b32 s9, s69, 7
	s_cmpk_gt_i32 s69, 0x1ff
	s_cselect_b64 s[52:53], -1, 0
	s_and_b64 s[6:7], s[52:53], exec
	s_cselect_b32 s24, 16, 0x80
	s_cselect_b32 s70, s8, s9
	s_lshl_b32 s15, s10, 4
	s_add_i32 s8, s70, s15
	s_ashr_i32 s9, s8, 31
	s_lshl_b64 s[8:9], s[8:9], 11
	v_and_b32_e32 v0, 63, v1
	s_load_dwordx4 s[36:39], s[0:1], 0x60
	s_load_dwordx2 s[26:27], s[0:1], 0x78
	s_waitcnt lgkmcnt(0)
	s_add_u32 s8, s42, s8
	v_lshlrev_b32_e32 v64, 4, v0
	s_addc_u32 s9, s43, s9
	v_lshl_add_u64 v[2:3], s[8:9], 0, v[64:65]
	s_lshl_b32 s8, s10, 7
	s_add_i32 s8, s8, 0
	v_cmp_eq_u32_e64 s[6:7], 0, v0
	s_add_i32 s16, s8, 0x20004
	s_cmp_ge_i32 s15, s24
	s_cbranch_scc1 .Lgst_done
	v_add_co_u32_e32 v60, vcc, 0x26c00000, v2
	s_nop 1
	v_addc_co_u32_e32 v61, vcc, 0, v3, vcc
	global_load_dwordx4 v[28:31], v[60:61], off
	global_load_dwordx4 v[32:35], v[60:61], off offset:1024
	global_load_dwordx4 v[36:39], v[60:61], off offset:2048
	global_load_dwordx4 v[40:43], v[60:61], off offset:3072
	v_add_co_u32_e32 v60, vcc, 0x1000, v60
	s_nop 1
	v_addc_co_u32_e32 v61, vcc, 0, v61, vcc
	global_load_dwordx4 v[44:47], v[60:61], off
	global_load_dwordx4 v[48:51], v[60:61], off offset:1024
	global_load_dwordx4 v[52:55], v[60:61], off offset:2048
	global_load_dwordx4 v[56:59], v[60:61], off offset:3072
	v_add_co_u32_e32 v60, vcc, 0x1000, v60
	s_nop 1
	v_addc_co_u32_e32 v61, vcc, 0, v61, vcc
	global_load_dwordx4 v[66:69], v[60:61], off
	global_load_dwordx4 v[70:73], v[60:61], off offset:1024
	global_load_dwordx4 v[74:77], v[60:61], off offset:2048
	global_load_dwordx4 v[78:81], v[60:61], off offset:3072
	v_add_co_u32_e32 v60, vcc, 0x1000, v60
	s_nop 1
	v_addc_co_u32_e32 v61, vcc, 0, v61, vcc
	global_load_dwordx4 v[82:85], v[60:61], off
	global_load_dwordx4 v[86:89], v[60:61], off offset:1024
	global_load_dwordx4 v[90:93], v[60:61], off offset:2048
	global_load_dwordx4 v[94:97], v[60:61], off offset:3072
	v_add_co_u32_e32 v60, vcc, 0x1000, v60
	s_nop 1
	v_addc_co_u32_e32 v61, vcc, 0, v61, vcc
	global_load_dwordx4 v[98:101], v[60:61], off
	global_load_dwordx4 v[102:105], v[60:61], off offset:1024
	global_load_dwordx4 v[122:125], v[60:61], off offset:2048
	global_load_dwordx4 v[126:129], v[60:61], off offset:3072
	v_add_co_u32_e32 v60, vcc, 0x1000, v60
	s_nop 1
	v_addc_co_u32_e32 v61, vcc, 0, v61, vcc
	global_load_dwordx4 v[130:133], v[60:61], off
	global_load_dwordx4 v[134:137], v[60:61], off offset:1024
	global_load_dwordx4 v[138:141], v[60:61], off offset:2048
	global_load_dwordx4 v[142:145], v[60:61], off offset:3072
	v_add_co_u32_e32 v60, vcc, 0x1000, v60
	s_nop 1
	v_addc_co_u32_e32 v61, vcc, 0, v61, vcc
	global_load_dwordx4 v[146:149], v[60:61], off
	global_load_dwordx4 v[150:153], v[60:61], off offset:1024
	global_load_dwordx4 v[154:157], v[60:61], off offset:2048
	global_load_dwordx4 v[158:161], v[60:61], off offset:3072
	v_add_co_u32_e32 v60, vcc, 0x1000, v60
	s_nop 1
	v_addc_co_u32_e32 v61, vcc, 0, v61, vcc
	global_load_dwordx4 v[162:165], v[60:61], off
	global_load_dwordx4 v[166:169], v[60:61], off offset:1024
	global_load_dwordx4 v[170:173], v[60:61], off offset:2048
	global_load_dwordx4 v[174:177], v[60:61], off offset:3072
	s_add_i32 s8, s16, -4
	v_mov_b32_e32 v62, s8
	s_waitcnt vmcnt(30)
	v_mov_b32_e32 v4, v28
	v_mov_b32_e32 v5, v29
	v_mov_b32_e32 v6, v30
	v_mov_b32_e32 v7, v31
	v_mov_b32_e32 v8, v32
	v_mov_b32_e32 v9, v33
	v_mov_b32_e32 v10, v34
	v_mov_b32_e32 v11, v35
	v_lshlrev_b32_e32 v13, 16, v4
	v_and_b32_e32 v14, 0xffff0000, v4
	v_lshlrev_b32_e32 v15, 16, v5
	v_and_b32_e32 v5, 0xffff0000, v5
	v_lshlrev_b32_e32 v16, 16, v6
	v_and_b32_e32 v6, 0xffff0000, v6
	v_lshlrev_b32_e32 v17, 16, v7
	v_and_b32_e32 v7, 0xffff0000, v7
	v_lshlrev_b32_e32 v18, 16, v8
	v_and_b32_e32 v8, 0xffff0000, v8
	v_lshlrev_b32_e32 v19, 16, v9
	v_and_b32_e32 v9, 0xffff0000, v9
	v_lshlrev_b32_e32 v20, 16, v10
	v_and_b32_e32 v10, 0xffff0000, v10
	v_lshlrev_b32_e32 v21, 16, v11
	v_and_b32_e32 v11, 0xffff0000, v11
	v_add_f32_e32 v22, v13, v14
	v_add_f32_e32 v23, v15, v5
	v_add_f32_e32 v24, v16, v6
	v_add_f32_e32 v25, v17, v7
	v_add_f32_e32 v26, v18, v8
	v_add_f32_e32 v27, v19, v9
	v_add_f32_e32 v12, v20, v10
	v_add_f32_e32 v4, v21, v11
	v_add_f32_e32 v22, v22, v23
	v_add_f32_e32 v24, v24, v25
	v_add_f32_e32 v26, v26, v27
	v_add_f32_e32 v4, v12, v4
	v_add_f32_e32 v22, v22, v24
	v_add_f32_e32 v4, v26, v4
	v_add_f32_e32 v4, v22, v4
	s_nop 1
	v_add_f32_dpp v4, v4, v4 row_ror:8 row_mask:0xf bank_mask:0xf bound_ctrl:1
	s_nop 1
	v_add_f32_dpp v4, v4, v4 row_ror:4 row_mask:0xf bank_mask:0xf bound_ctrl:1
	s_nop 1
	v_add_f32_dpp v4, v4, v4 row_ror:2 row_mask:0xf bank_mask:0xf bound_ctrl:1
	s_nop 1
	v_add_f32_dpp v4, v4, v4 row_ror:1 row_mask:0xf bank_mask:0xf bound_ctrl:1
	v_mov_b32_e32 v22, v4
	s_nop 1
	v_permlane16_swap_b32_e32 v4, v22
	v_add_f32_e32 v4, v4, v22
	v_mov_b32_e32 v22, v4
	s_nop 1
	v_permlane32_swap_b32_e32 v4, v22
	v_add_f32_e32 v4, v4, v22
	v_fmac_f32_e32 v13, 0xba800000, v4
	v_fmac_f32_e32 v14, 0xba800000, v4
	v_fmac_f32_e32 v15, 0xba800000, v4
	v_fmac_f32_e32 v5, 0xba800000, v4
	v_fmac_f32_e32 v16, 0xba800000, v4
	v_fmac_f32_e32 v6, 0xba800000, v4
	v_fmac_f32_e32 v17, 0xba800000, v4
	v_fmac_f32_e32 v7, 0xba800000, v4
	v_fmac_f32_e32 v18, 0xba800000, v4
	v_fmac_f32_e32 v8, 0xba800000, v4
	v_fmac_f32_e32 v19, 0xba800000, v4
	v_fmac_f32_e32 v9, 0xba800000, v4
	v_fmac_f32_e32 v20, 0xba800000, v4
	v_fmac_f32_e32 v10, 0xba800000, v4
	v_fmac_f32_e32 v21, 0xba800000, v4
	v_fmac_f32_e32 v11, 0xba800000, v4
	v_mul_f32_e32 v23, v13, v13
	v_fmac_f32_e32 v23, v14, v14
	v_fmac_f32_e32 v23, v15, v15
	v_fmac_f32_e32 v23, v5, v5
	v_fmac_f32_e32 v23, v16, v16
	v_fmac_f32_e32 v23, v6, v6
	v_fmac_f32_e32 v23, v17, v17
	v_fmac_f32_e32 v23, v7, v7
	v_fmac_f32_e32 v23, v18, v18
	v_fmac_f32_e32 v23, v8, v8
	v_fmac_f32_e32 v23, v19, v19
	v_fmac_f32_e32 v23, v9, v9
	v_fmac_f32_e32 v23, v20, v20
	v_fmac_f32_e32 v23, v10, v10
	v_fmac_f32_e32 v23, v21, v21
	v_fmac_f32_e32 v23, v11, v11
	s_nop 1
	v_add_f32_dpp v23, v23, v23 row_ror:8 row_mask:0xf bank_mask:0xf bound_ctrl:1
	s_nop 1
	v_add_f32_dpp v23, v23, v23 row_ror:4 row_mask:0xf bank_mask:0xf bound_ctrl:1
	s_nop 1
	v_add_f32_dpp v23, v23, v23 row_ror:2 row_mask:0xf bank_mask:0xf bound_ctrl:1
	s_nop 1
	v_add_f32_dpp v23, v23, v23 row_ror:1 row_mask:0xf bank_mask:0xf bound_ctrl:1
	v_mov_b32_e32 v22, v23
	s_nop 1
	v_permlane16_swap_b32_e32 v23, v22
	v_add_f32_e32 v23, v23, v22
	v_mov_b32_e32 v22, v23
	s_nop 1
	v_permlane32_swap_b32_e32 v23, v22
	v_add_f32_e32 v23, v23, v22
	s_and_saveexec_b64 s[12:13], s[6:7]
	v_mov_b32_e32 v5, v23
	v_fmamk_f32 v5, v5, 0x3a800000, v112
	v_mul_f32_e32 v6, 0x4f800000, v5
	v_cmp_gt_f32_e32 vcc, s67, v5
	v_mul_f32_e32 v4, 0x3a800000, v4
	s_nop 0
	v_cndmask_b32_e32 v5, v5, v6, vcc
	v_sqrt_f32_e32 v6, v5
	s_nop 0
	v_add_u32_e32 v7, -1, v6
	v_fma_f32 v9, -v7, v6, v5
	v_add_u32_e32 v8, 1, v6
	v_cmp_ge_f32_e64 s[8:9], 0, v9
	s_nop 1
	v_cndmask_b32_e64 v7, v6, v7, s[8:9]
	v_fma_f32 v6, -v8, v6, v5
	v_cmp_lt_f32_e64 s[8:9], 0, v6
	s_nop 1
	v_cndmask_b32_e64 v6, v7, v8, s[8:9]
	v_mul_f32_e32 v7, 0x37800000, v6
	v_cndmask_b32_e32 v6, v6, v7, vcc
	v_cmp_class_f32_e32 vcc, v5, v113
	s_nop 1
	v_cndmask_b32_e32 v5, v6, v5, vcc
	v_div_scale_f32 v6, s[8:9], v5, v5, 1.0
	v_rcp_f32_e32 v7, v6
	s_nop 0
	v_fma_f32 v8, -v6, v7, 1.0
	v_fmac_f32_e32 v7, v8, v7
	v_div_scale_f32 v8, vcc, 1.0, v5, 1.0
	v_mul_f32_e32 v9, v8, v7
	v_fma_f32 v10, -v6, v9, v8
	v_fmac_f32_e32 v9, v10, v7
	v_fma_f32 v6, -v6, v9, v8
	s_nop 1
	v_div_fmas_f32 v6, v6, v7, v9
	v_div_fixup_f32 v5, v6, v5, 1.0
	ds_write_b64 v62, v[4:5]
	s_or_b64 exec, exec, s[12:13]
	s_waitcnt vmcnt(28)
	v_mov_b32_e32 v4, v36
	v_mov_b32_e32 v5, v37
	v_mov_b32_e32 v6, v38
	v_mov_b32_e32 v7, v39
	v_mov_b32_e32 v8, v40
	v_mov_b32_e32 v9, v41
	v_mov_b32_e32 v10, v42
	v_mov_b32_e32 v11, v43
	v_lshlrev_b32_e32 v13, 16, v4
	v_and_b32_e32 v14, 0xffff0000, v4
	v_lshlrev_b32_e32 v15, 16, v5
	v_and_b32_e32 v5, 0xffff0000, v5
	v_lshlrev_b32_e32 v16, 16, v6
	v_and_b32_e32 v6, 0xffff0000, v6
	v_lshlrev_b32_e32 v17, 16, v7
	v_and_b32_e32 v7, 0xffff0000, v7
	v_lshlrev_b32_e32 v18, 16, v8
	v_and_b32_e32 v8, 0xffff0000, v8
	v_lshlrev_b32_e32 v19, 16, v9
	v_and_b32_e32 v9, 0xffff0000, v9
	v_lshlrev_b32_e32 v20, 16, v10
	v_and_b32_e32 v10, 0xffff0000, v10
	v_lshlrev_b32_e32 v21, 16, v11
	v_and_b32_e32 v11, 0xffff0000, v11
	v_add_f32_e32 v22, v13, v14
	v_add_f32_e32 v23, v15, v5
	v_add_f32_e32 v24, v16, v6
	v_add_f32_e32 v25, v17, v7
	v_add_f32_e32 v26, v18, v8
	v_add_f32_e32 v27, v19, v9
	v_add_f32_e32 v12, v20, v10
	v_add_f32_e32 v4, v21, v11
	v_add_f32_e32 v22, v22, v23
	v_add_f32_e32 v24, v24, v25
	v_add_f32_e32 v26, v26, v27
	v_add_f32_e32 v4, v12, v4
	v_add_f32_e32 v22, v22, v24
	v_add_f32_e32 v4, v26, v4
	v_add_f32_e32 v4, v22, v4
	s_nop 1
	v_add_f32_dpp v4, v4, v4 row_ror:8 row_mask:0xf bank_mask:0xf bound_ctrl:1
	s_nop 1
	v_add_f32_dpp v4, v4, v4 row_ror:4 row_mask:0xf bank_mask:0xf bound_ctrl:1
	s_nop 1
	v_add_f32_dpp v4, v4, v4 row_ror:2 row_mask:0xf bank_mask:0xf bound_ctrl:1
	s_nop 1
	v_add_f32_dpp v4, v4, v4 row_ror:1 row_mask:0xf bank_mask:0xf bound_ctrl:1
	v_mov_b32_e32 v22, v4
	s_nop 1
	v_permlane16_swap_b32_e32 v4, v22
	v_add_f32_e32 v4, v4, v22
	v_mov_b32_e32 v22, v4
	s_nop 1
	v_permlane32_swap_b32_e32 v4, v22
	v_add_f32_e32 v4, v4, v22
	v_fmac_f32_e32 v13, 0xba800000, v4
	v_fmac_f32_e32 v14, 0xba800000, v4
	v_fmac_f32_e32 v15, 0xba800000, v4
	v_fmac_f32_e32 v5, 0xba800000, v4
	v_fmac_f32_e32 v16, 0xba800000, v4
	v_fmac_f32_e32 v6, 0xba800000, v4
	v_fmac_f32_e32 v17, 0xba800000, v4
	v_fmac_f32_e32 v7, 0xba800000, v4
	v_fmac_f32_e32 v18, 0xba800000, v4
	v_fmac_f32_e32 v8, 0xba800000, v4
	v_fmac_f32_e32 v19, 0xba800000, v4
	v_fmac_f32_e32 v9, 0xba800000, v4
	v_fmac_f32_e32 v20, 0xba800000, v4
	v_fmac_f32_e32 v10, 0xba800000, v4
	v_fmac_f32_e32 v21, 0xba800000, v4
	v_fmac_f32_e32 v11, 0xba800000, v4
	v_mul_f32_e32 v23, v13, v13
	v_fmac_f32_e32 v23, v14, v14
	v_fmac_f32_e32 v23, v15, v15
	v_fmac_f32_e32 v23, v5, v5
	v_fmac_f32_e32 v23, v16, v16
	v_fmac_f32_e32 v23, v6, v6
	v_fmac_f32_e32 v23, v17, v17
	v_fmac_f32_e32 v23, v7, v7
	v_fmac_f32_e32 v23, v18, v18
	v_fmac_f32_e32 v23, v8, v8
	v_fmac_f32_e32 v23, v19, v19
	v_fmac_f32_e32 v23, v9, v9
	v_fmac_f32_e32 v23, v20, v20
	v_fmac_f32_e32 v23, v10, v10
	v_fmac_f32_e32 v23, v21, v21
	v_fmac_f32_e32 v23, v11, v11
	s_nop 1
	v_add_f32_dpp v23, v23, v23 row_ror:8 row_mask:0xf bank_mask:0xf bound_ctrl:1
	s_nop 1
	v_add_f32_dpp v23, v23, v23 row_ror:4 row_mask:0xf bank_mask:0xf bound_ctrl:1
	s_nop 1
	v_add_f32_dpp v23, v23, v23 row_ror:2 row_mask:0xf bank_mask:0xf bound_ctrl:1
	s_nop 1
	v_add_f32_dpp v23, v23, v23 row_ror:1 row_mask:0xf bank_mask:0xf bound_ctrl:1
	v_mov_b32_e32 v22, v23
	s_nop 1
	v_permlane16_swap_b32_e32 v23, v22
	v_add_f32_e32 v23, v23, v22
	v_mov_b32_e32 v22, v23
	s_nop 1
	v_permlane32_swap_b32_e32 v23, v22
	v_add_f32_e32 v23, v23, v22
	s_and_saveexec_b64 s[12:13], s[6:7]
	v_mov_b32_e32 v5, v23
	v_fmamk_f32 v5, v5, 0x3a800000, v112
	v_mul_f32_e32 v6, 0x4f800000, v5
	v_cmp_gt_f32_e32 vcc, s67, v5
	v_mul_f32_e32 v4, 0x3a800000, v4
	s_nop 0
	v_cndmask_b32_e32 v5, v5, v6, vcc
	v_sqrt_f32_e32 v6, v5
	s_nop 0
	v_add_u32_e32 v7, -1, v6
	v_fma_f32 v9, -v7, v6, v5
	v_add_u32_e32 v8, 1, v6
	v_cmp_ge_f32_e64 s[8:9], 0, v9
	s_nop 1
	v_cndmask_b32_e64 v7, v6, v7, s[8:9]
	v_fma_f32 v6, -v8, v6, v5
	v_cmp_lt_f32_e64 s[8:9], 0, v6
	s_nop 1
	v_cndmask_b32_e64 v6, v7, v8, s[8:9]
	v_mul_f32_e32 v7, 0x37800000, v6
	v_cndmask_b32_e32 v6, v6, v7, vcc
	v_cmp_class_f32_e32 vcc, v5, v113
	s_nop 1
	v_cndmask_b32_e32 v5, v6, v5, vcc
	v_div_scale_f32 v6, s[8:9], v5, v5, 1.0
	v_rcp_f32_e32 v7, v6
	s_nop 0
	v_fma_f32 v8, -v6, v7, 1.0
	v_fmac_f32_e32 v7, v8, v7
	v_div_scale_f32 v8, vcc, 1.0, v5, 1.0
	v_mul_f32_e32 v9, v8, v7
	v_fma_f32 v10, -v6, v9, v8
	v_fmac_f32_e32 v9, v10, v7
	v_fma_f32 v6, -v6, v9, v8
	s_nop 1
	v_div_fmas_f32 v6, v6, v7, v9
	v_div_fixup_f32 v5, v6, v5, 1.0
	ds_write_b64 v62, v[4:5] offset:8
	s_or_b64 exec, exec, s[12:13]
	s_waitcnt vmcnt(26)
	v_mov_b32_e32 v4, v44
	v_mov_b32_e32 v5, v45
	v_mov_b32_e32 v6, v46
	v_mov_b32_e32 v7, v47
	v_mov_b32_e32 v8, v48
	v_mov_b32_e32 v9, v49
	v_mov_b32_e32 v10, v50
	v_mov_b32_e32 v11, v51
	v_lshlrev_b32_e32 v13, 16, v4
	v_and_b32_e32 v14, 0xffff0000, v4
	v_lshlrev_b32_e32 v15, 16, v5
	v_and_b32_e32 v5, 0xffff0000, v5
	v_lshlrev_b32_e32 v16, 16, v6
	v_and_b32_e32 v6, 0xffff0000, v6
	v_lshlrev_b32_e32 v17, 16, v7
	v_and_b32_e32 v7, 0xffff0000, v7
	v_lshlrev_b32_e32 v18, 16, v8
	v_and_b32_e32 v8, 0xffff0000, v8
	v_lshlrev_b32_e32 v19, 16, v9
	v_and_b32_e32 v9, 0xffff0000, v9
	v_lshlrev_b32_e32 v20, 16, v10
	v_and_b32_e32 v10, 0xffff0000, v10
	v_lshlrev_b32_e32 v21, 16, v11
	v_and_b32_e32 v11, 0xffff0000, v11
	v_add_f32_e32 v22, v13, v14
	v_add_f32_e32 v23, v15, v5
	v_add_f32_e32 v24, v16, v6
	v_add_f32_e32 v25, v17, v7
	v_add_f32_e32 v26, v18, v8
	v_add_f32_e32 v27, v19, v9
	v_add_f32_e32 v12, v20, v10
	v_add_f32_e32 v4, v21, v11
	v_add_f32_e32 v22, v22, v23
	v_add_f32_e32 v24, v24, v25
	v_add_f32_e32 v26, v26, v27
	v_add_f32_e32 v4, v12, v4
	v_add_f32_e32 v22, v22, v24
	v_add_f32_e32 v4, v26, v4
	v_add_f32_e32 v4, v22, v4
	s_nop 1
	v_add_f32_dpp v4, v4, v4 row_ror:8 row_mask:0xf bank_mask:0xf bound_ctrl:1
	s_nop 1
	v_add_f32_dpp v4, v4, v4 row_ror:4 row_mask:0xf bank_mask:0xf bound_ctrl:1
	s_nop 1
	v_add_f32_dpp v4, v4, v4 row_ror:2 row_mask:0xf bank_mask:0xf bound_ctrl:1
	s_nop 1
	v_add_f32_dpp v4, v4, v4 row_ror:1 row_mask:0xf bank_mask:0xf bound_ctrl:1
	v_mov_b32_e32 v22, v4
	s_nop 1
	v_permlane16_swap_b32_e32 v4, v22
	v_add_f32_e32 v4, v4, v22
	v_mov_b32_e32 v22, v4
	s_nop 1
	v_permlane32_swap_b32_e32 v4, v22
	v_add_f32_e32 v4, v4, v22
	v_fmac_f32_e32 v13, 0xba800000, v4
	v_fmac_f32_e32 v14, 0xba800000, v4
	v_fmac_f32_e32 v15, 0xba800000, v4
	v_fmac_f32_e32 v5, 0xba800000, v4
	v_fmac_f32_e32 v16, 0xba800000, v4
	v_fmac_f32_e32 v6, 0xba800000, v4
	v_fmac_f32_e32 v17, 0xba800000, v4
	v_fmac_f32_e32 v7, 0xba800000, v4
	v_fmac_f32_e32 v18, 0xba800000, v4
	v_fmac_f32_e32 v8, 0xba800000, v4
	v_fmac_f32_e32 v19, 0xba800000, v4
	v_fmac_f32_e32 v9, 0xba800000, v4
	v_fmac_f32_e32 v20, 0xba800000, v4
	v_fmac_f32_e32 v10, 0xba800000, v4
	v_fmac_f32_e32 v21, 0xba800000, v4
	v_fmac_f32_e32 v11, 0xba800000, v4
	v_mul_f32_e32 v23, v13, v13
	v_fmac_f32_e32 v23, v14, v14
	v_fmac_f32_e32 v23, v15, v15
	v_fmac_f32_e32 v23, v5, v5
	v_fmac_f32_e32 v23, v16, v16
	v_fmac_f32_e32 v23, v6, v6
	v_fmac_f32_e32 v23, v17, v17
	v_fmac_f32_e32 v23, v7, v7
	v_fmac_f32_e32 v23, v18, v18
	v_fmac_f32_e32 v23, v8, v8
	v_fmac_f32_e32 v23, v19, v19
	v_fmac_f32_e32 v23, v9, v9
	v_fmac_f32_e32 v23, v20, v20
	v_fmac_f32_e32 v23, v10, v10
	v_fmac_f32_e32 v23, v21, v21
	v_fmac_f32_e32 v23, v11, v11
	s_nop 1
	v_add_f32_dpp v23, v23, v23 row_ror:8 row_mask:0xf bank_mask:0xf bound_ctrl:1
	s_nop 1
	v_add_f32_dpp v23, v23, v23 row_ror:4 row_mask:0xf bank_mask:0xf bound_ctrl:1
	s_nop 1
	v_add_f32_dpp v23, v23, v23 row_ror:2 row_mask:0xf bank_mask:0xf bound_ctrl:1
	s_nop 1
	v_add_f32_dpp v23, v23, v23 row_ror:1 row_mask:0xf bank_mask:0xf bound_ctrl:1
	v_mov_b32_e32 v22, v23
	s_nop 1
	v_permlane16_swap_b32_e32 v23, v22
	v_add_f32_e32 v23, v23, v22
	v_mov_b32_e32 v22, v23
	s_nop 1
	v_permlane32_swap_b32_e32 v23, v22
	v_add_f32_e32 v23, v23, v22
	s_and_saveexec_b64 s[12:13], s[6:7]
	v_mov_b32_e32 v5, v23
	v_fmamk_f32 v5, v5, 0x3a800000, v112
	v_mul_f32_e32 v6, 0x4f800000, v5
	v_cmp_gt_f32_e32 vcc, s67, v5
	v_mul_f32_e32 v4, 0x3a800000, v4
	s_nop 0
	v_cndmask_b32_e32 v5, v5, v6, vcc
	v_sqrt_f32_e32 v6, v5
	s_nop 0
	v_add_u32_e32 v7, -1, v6
	v_fma_f32 v9, -v7, v6, v5
	v_add_u32_e32 v8, 1, v6
	v_cmp_ge_f32_e64 s[8:9], 0, v9
	s_nop 1
	v_cndmask_b32_e64 v7, v6, v7, s[8:9]
	v_fma_f32 v6, -v8, v6, v5
	v_cmp_lt_f32_e64 s[8:9], 0, v6
	s_nop 1
	v_cndmask_b32_e64 v6, v7, v8, s[8:9]
	v_mul_f32_e32 v7, 0x37800000, v6
	v_cndmask_b32_e32 v6, v6, v7, vcc
	v_cmp_class_f32_e32 vcc, v5, v113
	s_nop 1
	v_cndmask_b32_e32 v5, v6, v5, vcc
	v_div_scale_f32 v6, s[8:9], v5, v5, 1.0
	v_rcp_f32_e32 v7, v6
	s_nop 0
	v_fma_f32 v8, -v6, v7, 1.0
	v_fmac_f32_e32 v7, v8, v7
	v_div_scale_f32 v8, vcc, 1.0, v5, 1.0
	v_mul_f32_e32 v9, v8, v7
	v_fma_f32 v10, -v6, v9, v8
	v_fmac_f32_e32 v9, v10, v7
	v_fma_f32 v6, -v6, v9, v8
	s_nop 1
	v_div_fmas_f32 v6, v6, v7, v9
	v_div_fixup_f32 v5, v6, v5, 1.0
	ds_write_b64 v62, v[4:5] offset:16
	s_or_b64 exec, exec, s[12:13]
	s_waitcnt vmcnt(24)
	v_mov_b32_e32 v4, v52
	v_mov_b32_e32 v5, v53
	v_mov_b32_e32 v6, v54
	v_mov_b32_e32 v7, v55
	v_mov_b32_e32 v8, v56
	v_mov_b32_e32 v9, v57
	v_mov_b32_e32 v10, v58
	v_mov_b32_e32 v11, v59
	v_lshlrev_b32_e32 v13, 16, v4
	v_and_b32_e32 v14, 0xffff0000, v4
	v_lshlrev_b32_e32 v15, 16, v5
	v_and_b32_e32 v5, 0xffff0000, v5
	v_lshlrev_b32_e32 v16, 16, v6
	v_and_b32_e32 v6, 0xffff0000, v6
	v_lshlrev_b32_e32 v17, 16, v7
	v_and_b32_e32 v7, 0xffff0000, v7
	v_lshlrev_b32_e32 v18, 16, v8
	v_and_b32_e32 v8, 0xffff0000, v8
	v_lshlrev_b32_e32 v19, 16, v9
	v_and_b32_e32 v9, 0xffff0000, v9
	v_lshlrev_b32_e32 v20, 16, v10
	v_and_b32_e32 v10, 0xffff0000, v10
	v_lshlrev_b32_e32 v21, 16, v11
	v_and_b32_e32 v11, 0xffff0000, v11
	v_add_f32_e32 v22, v13, v14
	v_add_f32_e32 v23, v15, v5
	v_add_f32_e32 v24, v16, v6
	v_add_f32_e32 v25, v17, v7
	v_add_f32_e32 v26, v18, v8
	v_add_f32_e32 v27, v19, v9
	v_add_f32_e32 v12, v20, v10
	v_add_f32_e32 v4, v21, v11
	v_add_f32_e32 v22, v22, v23
	v_add_f32_e32 v24, v24, v25
	v_add_f32_e32 v26, v26, v27
	v_add_f32_e32 v4, v12, v4
	v_add_f32_e32 v22, v22, v24
	v_add_f32_e32 v4, v26, v4
	v_add_f32_e32 v4, v22, v4
	s_nop 1
	v_add_f32_dpp v4, v4, v4 row_ror:8 row_mask:0xf bank_mask:0xf bound_ctrl:1
	s_nop 1
	v_add_f32_dpp v4, v4, v4 row_ror:4 row_mask:0xf bank_mask:0xf bound_ctrl:1
	s_nop 1
	v_add_f32_dpp v4, v4, v4 row_ror:2 row_mask:0xf bank_mask:0xf bound_ctrl:1
	s_nop 1
	v_add_f32_dpp v4, v4, v4 row_ror:1 row_mask:0xf bank_mask:0xf bound_ctrl:1
	v_mov_b32_e32 v22, v4
	s_nop 1
	v_permlane16_swap_b32_e32 v4, v22
	v_add_f32_e32 v4, v4, v22
	v_mov_b32_e32 v22, v4
	s_nop 1
	v_permlane32_swap_b32_e32 v4, v22
	v_add_f32_e32 v4, v4, v22
	v_fmac_f32_e32 v13, 0xba800000, v4
	v_fmac_f32_e32 v14, 0xba800000, v4
	v_fmac_f32_e32 v15, 0xba800000, v4
	v_fmac_f32_e32 v5, 0xba800000, v4
	v_fmac_f32_e32 v16, 0xba800000, v4
	v_fmac_f32_e32 v6, 0xba800000, v4
	v_fmac_f32_e32 v17, 0xba800000, v4
	v_fmac_f32_e32 v7, 0xba800000, v4
	v_fmac_f32_e32 v18, 0xba800000, v4
	v_fmac_f32_e32 v8, 0xba800000, v4
	v_fmac_f32_e32 v19, 0xba800000, v4
	v_fmac_f32_e32 v9, 0xba800000, v4
	v_fmac_f32_e32 v20, 0xba800000, v4
	v_fmac_f32_e32 v10, 0xba800000, v4
	v_fmac_f32_e32 v21, 0xba800000, v4
	v_fmac_f32_e32 v11, 0xba800000, v4
	v_mul_f32_e32 v23, v13, v13
	v_fmac_f32_e32 v23, v14, v14
	v_fmac_f32_e32 v23, v15, v15
	v_fmac_f32_e32 v23, v5, v5
	v_fmac_f32_e32 v23, v16, v16
	v_fmac_f32_e32 v23, v6, v6
	v_fmac_f32_e32 v23, v17, v17
	v_fmac_f32_e32 v23, v7, v7
	v_fmac_f32_e32 v23, v18, v18
	v_fmac_f32_e32 v23, v8, v8
	v_fmac_f32_e32 v23, v19, v19
	v_fmac_f32_e32 v23, v9, v9
	v_fmac_f32_e32 v23, v20, v20
	v_fmac_f32_e32 v23, v10, v10
	v_fmac_f32_e32 v23, v21, v21
	v_fmac_f32_e32 v23, v11, v11
	s_nop 1
	v_add_f32_dpp v23, v23, v23 row_ror:8 row_mask:0xf bank_mask:0xf bound_ctrl:1
	s_nop 1
	v_add_f32_dpp v23, v23, v23 row_ror:4 row_mask:0xf bank_mask:0xf bound_ctrl:1
	s_nop 1
	v_add_f32_dpp v23, v23, v23 row_ror:2 row_mask:0xf bank_mask:0xf bound_ctrl:1
	s_nop 1
	v_add_f32_dpp v23, v23, v23 row_ror:1 row_mask:0xf bank_mask:0xf bound_ctrl:1
	v_mov_b32_e32 v22, v23
	s_nop 1
	v_permlane16_swap_b32_e32 v23, v22
	v_add_f32_e32 v23, v23, v22
	v_mov_b32_e32 v22, v23
	s_nop 1
	v_permlane32_swap_b32_e32 v23, v22
	v_add_f32_e32 v23, v23, v22
	s_and_saveexec_b64 s[12:13], s[6:7]
	v_mov_b32_e32 v5, v23
	v_fmamk_f32 v5, v5, 0x3a800000, v112
	v_mul_f32_e32 v6, 0x4f800000, v5
	v_cmp_gt_f32_e32 vcc, s67, v5
	v_mul_f32_e32 v4, 0x3a800000, v4
	s_nop 0
	v_cndmask_b32_e32 v5, v5, v6, vcc
	v_sqrt_f32_e32 v6, v5
	s_nop 0
	v_add_u32_e32 v7, -1, v6
	v_fma_f32 v9, -v7, v6, v5
	v_add_u32_e32 v8, 1, v6
	v_cmp_ge_f32_e64 s[8:9], 0, v9
	s_nop 1
	v_cndmask_b32_e64 v7, v6, v7, s[8:9]
	v_fma_f32 v6, -v8, v6, v5
	v_cmp_lt_f32_e64 s[8:9], 0, v6
	s_nop 1
	v_cndmask_b32_e64 v6, v7, v8, s[8:9]
	v_mul_f32_e32 v7, 0x37800000, v6
	v_cndmask_b32_e32 v6, v6, v7, vcc
	v_cmp_class_f32_e32 vcc, v5, v113
	s_nop 1
	v_cndmask_b32_e32 v5, v6, v5, vcc
	v_div_scale_f32 v6, s[8:9], v5, v5, 1.0
	v_rcp_f32_e32 v7, v6
	s_nop 0
	v_fma_f32 v8, -v6, v7, 1.0
	v_fmac_f32_e32 v7, v8, v7
	v_div_scale_f32 v8, vcc, 1.0, v5, 1.0
	v_mul_f32_e32 v9, v8, v7
	v_fma_f32 v10, -v6, v9, v8
	v_fmac_f32_e32 v9, v10, v7
	v_fma_f32 v6, -v6, v9, v8
	s_nop 1
	v_div_fmas_f32 v6, v6, v7, v9
	v_div_fixup_f32 v5, v6, v5, 1.0
	ds_write_b64 v62, v[4:5] offset:24
	s_or_b64 exec, exec, s[12:13]
	s_waitcnt vmcnt(22)
	v_mov_b32_e32 v4, v66
	v_mov_b32_e32 v5, v67
	v_mov_b32_e32 v6, v68
	v_mov_b32_e32 v7, v69
	v_mov_b32_e32 v8, v70
	v_mov_b32_e32 v9, v71
	v_mov_b32_e32 v10, v72
	v_mov_b32_e32 v11, v73
	v_lshlrev_b32_e32 v13, 16, v4
	v_and_b32_e32 v14, 0xffff0000, v4
	v_lshlrev_b32_e32 v15, 16, v5
	v_and_b32_e32 v5, 0xffff0000, v5
	v_lshlrev_b32_e32 v16, 16, v6
	v_and_b32_e32 v6, 0xffff0000, v6
	v_lshlrev_b32_e32 v17, 16, v7
	v_and_b32_e32 v7, 0xffff0000, v7
	v_lshlrev_b32_e32 v18, 16, v8
	v_and_b32_e32 v8, 0xffff0000, v8
	v_lshlrev_b32_e32 v19, 16, v9
	v_and_b32_e32 v9, 0xffff0000, v9
	v_lshlrev_b32_e32 v20, 16, v10
	v_and_b32_e32 v10, 0xffff0000, v10
	v_lshlrev_b32_e32 v21, 16, v11
	v_and_b32_e32 v11, 0xffff0000, v11
	v_add_f32_e32 v22, v13, v14
	v_add_f32_e32 v23, v15, v5
	v_add_f32_e32 v24, v16, v6
	v_add_f32_e32 v25, v17, v7
	v_add_f32_e32 v26, v18, v8
	v_add_f32_e32 v27, v19, v9
	v_add_f32_e32 v12, v20, v10
	v_add_f32_e32 v4, v21, v11
	v_add_f32_e32 v22, v22, v23
	v_add_f32_e32 v24, v24, v25
	v_add_f32_e32 v26, v26, v27
	v_add_f32_e32 v4, v12, v4
	v_add_f32_e32 v22, v22, v24
	v_add_f32_e32 v4, v26, v4
	v_add_f32_e32 v4, v22, v4
	s_nop 1
	v_add_f32_dpp v4, v4, v4 row_ror:8 row_mask:0xf bank_mask:0xf bound_ctrl:1
	s_nop 1
	v_add_f32_dpp v4, v4, v4 row_ror:4 row_mask:0xf bank_mask:0xf bound_ctrl:1
	s_nop 1
	v_add_f32_dpp v4, v4, v4 row_ror:2 row_mask:0xf bank_mask:0xf bound_ctrl:1
	s_nop 1
	v_add_f32_dpp v4, v4, v4 row_ror:1 row_mask:0xf bank_mask:0xf bound_ctrl:1
	v_mov_b32_e32 v22, v4
	s_nop 1
	v_permlane16_swap_b32_e32 v4, v22
	v_add_f32_e32 v4, v4, v22
	v_mov_b32_e32 v22, v4
	s_nop 1
	v_permlane32_swap_b32_e32 v4, v22
	v_add_f32_e32 v4, v4, v22
	v_fmac_f32_e32 v13, 0xba800000, v4
	v_fmac_f32_e32 v14, 0xba800000, v4
	v_fmac_f32_e32 v15, 0xba800000, v4
	v_fmac_f32_e32 v5, 0xba800000, v4
	v_fmac_f32_e32 v16, 0xba800000, v4
	v_fmac_f32_e32 v6, 0xba800000, v4
	v_fmac_f32_e32 v17, 0xba800000, v4
	v_fmac_f32_e32 v7, 0xba800000, v4
	v_fmac_f32_e32 v18, 0xba800000, v4
	v_fmac_f32_e32 v8, 0xba800000, v4
	v_fmac_f32_e32 v19, 0xba800000, v4
	v_fmac_f32_e32 v9, 0xba800000, v4
	v_fmac_f32_e32 v20, 0xba800000, v4
	v_fmac_f32_e32 v10, 0xba800000, v4
	v_fmac_f32_e32 v21, 0xba800000, v4
	v_fmac_f32_e32 v11, 0xba800000, v4
	v_mul_f32_e32 v23, v13, v13
	v_fmac_f32_e32 v23, v14, v14
	v_fmac_f32_e32 v23, v15, v15
	v_fmac_f32_e32 v23, v5, v5
	v_fmac_f32_e32 v23, v16, v16
	v_fmac_f32_e32 v23, v6, v6
	v_fmac_f32_e32 v23, v17, v17
	v_fmac_f32_e32 v23, v7, v7
	v_fmac_f32_e32 v23, v18, v18
	v_fmac_f32_e32 v23, v8, v8
	v_fmac_f32_e32 v23, v19, v19
	v_fmac_f32_e32 v23, v9, v9
	v_fmac_f32_e32 v23, v20, v20
	v_fmac_f32_e32 v23, v10, v10
	v_fmac_f32_e32 v23, v21, v21
	v_fmac_f32_e32 v23, v11, v11
	s_nop 1
	v_add_f32_dpp v23, v23, v23 row_ror:8 row_mask:0xf bank_mask:0xf bound_ctrl:1
	s_nop 1
	v_add_f32_dpp v23, v23, v23 row_ror:4 row_mask:0xf bank_mask:0xf bound_ctrl:1
	s_nop 1
	v_add_f32_dpp v23, v23, v23 row_ror:2 row_mask:0xf bank_mask:0xf bound_ctrl:1
	s_nop 1
	v_add_f32_dpp v23, v23, v23 row_ror:1 row_mask:0xf bank_mask:0xf bound_ctrl:1
	v_mov_b32_e32 v22, v23
	s_nop 1
	v_permlane16_swap_b32_e32 v23, v22
	v_add_f32_e32 v23, v23, v22
	v_mov_b32_e32 v22, v23
	s_nop 1
	v_permlane32_swap_b32_e32 v23, v22
	v_add_f32_e32 v23, v23, v22
	s_and_saveexec_b64 s[12:13], s[6:7]
	v_mov_b32_e32 v5, v23
	v_fmamk_f32 v5, v5, 0x3a800000, v112
	v_mul_f32_e32 v6, 0x4f800000, v5
	v_cmp_gt_f32_e32 vcc, s67, v5
	v_mul_f32_e32 v4, 0x3a800000, v4
	s_nop 0
	v_cndmask_b32_e32 v5, v5, v6, vcc
	v_sqrt_f32_e32 v6, v5
	s_nop 0
	v_add_u32_e32 v7, -1, v6
	v_fma_f32 v9, -v7, v6, v5
	v_add_u32_e32 v8, 1, v6
	v_cmp_ge_f32_e64 s[8:9], 0, v9
	s_nop 1
	v_cndmask_b32_e64 v7, v6, v7, s[8:9]
	v_fma_f32 v6, -v8, v6, v5
	v_cmp_lt_f32_e64 s[8:9], 0, v6
	s_nop 1
	v_cndmask_b32_e64 v6, v7, v8, s[8:9]
	v_mul_f32_e32 v7, 0x37800000, v6
	v_cndmask_b32_e32 v6, v6, v7, vcc
	v_cmp_class_f32_e32 vcc, v5, v113
	s_nop 1
	v_cndmask_b32_e32 v5, v6, v5, vcc
	v_div_scale_f32 v6, s[8:9], v5, v5, 1.0
	v_rcp_f32_e32 v7, v6
	s_nop 0
	v_fma_f32 v8, -v6, v7, 1.0
	v_fmac_f32_e32 v7, v8, v7
	v_div_scale_f32 v8, vcc, 1.0, v5, 1.0
	v_mul_f32_e32 v9, v8, v7
	v_fma_f32 v10, -v6, v9, v8
	v_fmac_f32_e32 v9, v10, v7
	v_fma_f32 v6, -v6, v9, v8
	s_nop 1
	v_div_fmas_f32 v6, v6, v7, v9
	v_div_fixup_f32 v5, v6, v5, 1.0
	ds_write_b64 v62, v[4:5] offset:32
	s_or_b64 exec, exec, s[12:13]
	s_waitcnt vmcnt(20)
	v_mov_b32_e32 v4, v74
	v_mov_b32_e32 v5, v75
	v_mov_b32_e32 v6, v76
	v_mov_b32_e32 v7, v77
	v_mov_b32_e32 v8, v78
	v_mov_b32_e32 v9, v79
	v_mov_b32_e32 v10, v80
	v_mov_b32_e32 v11, v81
	v_lshlrev_b32_e32 v13, 16, v4
	v_and_b32_e32 v14, 0xffff0000, v4
	v_lshlrev_b32_e32 v15, 16, v5
	v_and_b32_e32 v5, 0xffff0000, v5
	v_lshlrev_b32_e32 v16, 16, v6
	v_and_b32_e32 v6, 0xffff0000, v6
	v_lshlrev_b32_e32 v17, 16, v7
	v_and_b32_e32 v7, 0xffff0000, v7
	v_lshlrev_b32_e32 v18, 16, v8
	v_and_b32_e32 v8, 0xffff0000, v8
	v_lshlrev_b32_e32 v19, 16, v9
	v_and_b32_e32 v9, 0xffff0000, v9
	v_lshlrev_b32_e32 v20, 16, v10
	v_and_b32_e32 v10, 0xffff0000, v10
	v_lshlrev_b32_e32 v21, 16, v11
	v_and_b32_e32 v11, 0xffff0000, v11
	v_add_f32_e32 v22, v13, v14
	v_add_f32_e32 v23, v15, v5
	v_add_f32_e32 v24, v16, v6
	v_add_f32_e32 v25, v17, v7
	v_add_f32_e32 v26, v18, v8
	v_add_f32_e32 v27, v19, v9
	v_add_f32_e32 v12, v20, v10
	v_add_f32_e32 v4, v21, v11
	v_add_f32_e32 v22, v22, v23
	v_add_f32_e32 v24, v24, v25
	v_add_f32_e32 v26, v26, v27
	v_add_f32_e32 v4, v12, v4
	v_add_f32_e32 v22, v22, v24
	v_add_f32_e32 v4, v26, v4
	v_add_f32_e32 v4, v22, v4
	s_nop 1
	v_add_f32_dpp v4, v4, v4 row_ror:8 row_mask:0xf bank_mask:0xf bound_ctrl:1
	s_nop 1
	v_add_f32_dpp v4, v4, v4 row_ror:4 row_mask:0xf bank_mask:0xf bound_ctrl:1
	s_nop 1
	v_add_f32_dpp v4, v4, v4 row_ror:2 row_mask:0xf bank_mask:0xf bound_ctrl:1
	s_nop 1
	v_add_f32_dpp v4, v4, v4 row_ror:1 row_mask:0xf bank_mask:0xf bound_ctrl:1
	v_mov_b32_e32 v22, v4
	s_nop 1
	v_permlane16_swap_b32_e32 v4, v22
	v_add_f32_e32 v4, v4, v22
	v_mov_b32_e32 v22, v4
	s_nop 1
	v_permlane32_swap_b32_e32 v4, v22
	v_add_f32_e32 v4, v4, v22
	v_fmac_f32_e32 v13, 0xba800000, v4
	v_fmac_f32_e32 v14, 0xba800000, v4
	v_fmac_f32_e32 v15, 0xba800000, v4
	v_fmac_f32_e32 v5, 0xba800000, v4
	v_fmac_f32_e32 v16, 0xba800000, v4
	v_fmac_f32_e32 v6, 0xba800000, v4
	v_fmac_f32_e32 v17, 0xba800000, v4
	v_fmac_f32_e32 v7, 0xba800000, v4
	v_fmac_f32_e32 v18, 0xba800000, v4
	v_fmac_f32_e32 v8, 0xba800000, v4
	v_fmac_f32_e32 v19, 0xba800000, v4
	v_fmac_f32_e32 v9, 0xba800000, v4
	v_fmac_f32_e32 v20, 0xba800000, v4
	v_fmac_f32_e32 v10, 0xba800000, v4
	v_fmac_f32_e32 v21, 0xba800000, v4
	v_fmac_f32_e32 v11, 0xba800000, v4
	v_mul_f32_e32 v23, v13, v13
	v_fmac_f32_e32 v23, v14, v14
	v_fmac_f32_e32 v23, v15, v15
	v_fmac_f32_e32 v23, v5, v5
	v_fmac_f32_e32 v23, v16, v16
	v_fmac_f32_e32 v23, v6, v6
	v_fmac_f32_e32 v23, v17, v17
	v_fmac_f32_e32 v23, v7, v7
	v_fmac_f32_e32 v23, v18, v18
	v_fmac_f32_e32 v23, v8, v8
	v_fmac_f32_e32 v23, v19, v19
	v_fmac_f32_e32 v23, v9, v9
	v_fmac_f32_e32 v23, v20, v20
	v_fmac_f32_e32 v23, v10, v10
	v_fmac_f32_e32 v23, v21, v21
	v_fmac_f32_e32 v23, v11, v11
	s_nop 1
	v_add_f32_dpp v23, v23, v23 row_ror:8 row_mask:0xf bank_mask:0xf bound_ctrl:1
	s_nop 1
	v_add_f32_dpp v23, v23, v23 row_ror:4 row_mask:0xf bank_mask:0xf bound_ctrl:1
	s_nop 1
	v_add_f32_dpp v23, v23, v23 row_ror:2 row_mask:0xf bank_mask:0xf bound_ctrl:1
	s_nop 1
	v_add_f32_dpp v23, v23, v23 row_ror:1 row_mask:0xf bank_mask:0xf bound_ctrl:1
	v_mov_b32_e32 v22, v23
	s_nop 1
	v_permlane16_swap_b32_e32 v23, v22
	v_add_f32_e32 v23, v23, v22
	v_mov_b32_e32 v22, v23
	s_nop 1
	v_permlane32_swap_b32_e32 v23, v22
	v_add_f32_e32 v23, v23, v22
	s_and_saveexec_b64 s[12:13], s[6:7]
	v_mov_b32_e32 v5, v23
	v_fmamk_f32 v5, v5, 0x3a800000, v112
	v_mul_f32_e32 v6, 0x4f800000, v5
	v_cmp_gt_f32_e32 vcc, s67, v5
	v_mul_f32_e32 v4, 0x3a800000, v4
	s_nop 0
	v_cndmask_b32_e32 v5, v5, v6, vcc
	v_sqrt_f32_e32 v6, v5
	s_nop 0
	v_add_u32_e32 v7, -1, v6
	v_fma_f32 v9, -v7, v6, v5
	v_add_u32_e32 v8, 1, v6
	v_cmp_ge_f32_e64 s[8:9], 0, v9
	s_nop 1
	v_cndmask_b32_e64 v7, v6, v7, s[8:9]
	v_fma_f32 v6, -v8, v6, v5
	v_cmp_lt_f32_e64 s[8:9], 0, v6
	s_nop 1
	v_cndmask_b32_e64 v6, v7, v8, s[8:9]
	v_mul_f32_e32 v7, 0x37800000, v6
	v_cndmask_b32_e32 v6, v6, v7, vcc
	v_cmp_class_f32_e32 vcc, v5, v113
	s_nop 1
	v_cndmask_b32_e32 v5, v6, v5, vcc
	v_div_scale_f32 v6, s[8:9], v5, v5, 1.0
	v_rcp_f32_e32 v7, v6
	s_nop 0
	v_fma_f32 v8, -v6, v7, 1.0
	v_fmac_f32_e32 v7, v8, v7
	v_div_scale_f32 v8, vcc, 1.0, v5, 1.0
	v_mul_f32_e32 v9, v8, v7
	v_fma_f32 v10, -v6, v9, v8
	v_fmac_f32_e32 v9, v10, v7
	v_fma_f32 v6, -v6, v9, v8
	s_nop 1
	v_div_fmas_f32 v6, v6, v7, v9
	v_div_fixup_f32 v5, v6, v5, 1.0
	ds_write_b64 v62, v[4:5] offset:40
	s_or_b64 exec, exec, s[12:13]
	s_waitcnt vmcnt(18)
	v_mov_b32_e32 v4, v82
	v_mov_b32_e32 v5, v83
	v_mov_b32_e32 v6, v84
	v_mov_b32_e32 v7, v85
	v_mov_b32_e32 v8, v86
	v_mov_b32_e32 v9, v87
	v_mov_b32_e32 v10, v88
	v_mov_b32_e32 v11, v89
	v_lshlrev_b32_e32 v13, 16, v4
	v_and_b32_e32 v14, 0xffff0000, v4
	v_lshlrev_b32_e32 v15, 16, v5
	v_and_b32_e32 v5, 0xffff0000, v5
	v_lshlrev_b32_e32 v16, 16, v6
	v_and_b32_e32 v6, 0xffff0000, v6
	v_lshlrev_b32_e32 v17, 16, v7
	v_and_b32_e32 v7, 0xffff0000, v7
	v_lshlrev_b32_e32 v18, 16, v8
	v_and_b32_e32 v8, 0xffff0000, v8
	v_lshlrev_b32_e32 v19, 16, v9
	v_and_b32_e32 v9, 0xffff0000, v9
	v_lshlrev_b32_e32 v20, 16, v10
	v_and_b32_e32 v10, 0xffff0000, v10
	v_lshlrev_b32_e32 v21, 16, v11
	v_and_b32_e32 v11, 0xffff0000, v11
	v_add_f32_e32 v22, v13, v14
	v_add_f32_e32 v23, v15, v5
	v_add_f32_e32 v24, v16, v6
	v_add_f32_e32 v25, v17, v7
	v_add_f32_e32 v26, v18, v8
	v_add_f32_e32 v27, v19, v9
	v_add_f32_e32 v12, v20, v10
	v_add_f32_e32 v4, v21, v11
	v_add_f32_e32 v22, v22, v23
	v_add_f32_e32 v24, v24, v25
	v_add_f32_e32 v26, v26, v27
	v_add_f32_e32 v4, v12, v4
	v_add_f32_e32 v22, v22, v24
	v_add_f32_e32 v4, v26, v4
	v_add_f32_e32 v4, v22, v4
	s_nop 1
	v_add_f32_dpp v4, v4, v4 row_ror:8 row_mask:0xf bank_mask:0xf bound_ctrl:1
	s_nop 1
	v_add_f32_dpp v4, v4, v4 row_ror:4 row_mask:0xf bank_mask:0xf bound_ctrl:1
	s_nop 1
	v_add_f32_dpp v4, v4, v4 row_ror:2 row_mask:0xf bank_mask:0xf bound_ctrl:1
	s_nop 1
	v_add_f32_dpp v4, v4, v4 row_ror:1 row_mask:0xf bank_mask:0xf bound_ctrl:1
	v_mov_b32_e32 v22, v4
	s_nop 1
	v_permlane16_swap_b32_e32 v4, v22
	v_add_f32_e32 v4, v4, v22
	v_mov_b32_e32 v22, v4
	s_nop 1
	v_permlane32_swap_b32_e32 v4, v22
	v_add_f32_e32 v4, v4, v22
	v_fmac_f32_e32 v13, 0xba800000, v4
	v_fmac_f32_e32 v14, 0xba800000, v4
	v_fmac_f32_e32 v15, 0xba800000, v4
	v_fmac_f32_e32 v5, 0xba800000, v4
	v_fmac_f32_e32 v16, 0xba800000, v4
	v_fmac_f32_e32 v6, 0xba800000, v4
	v_fmac_f32_e32 v17, 0xba800000, v4
	v_fmac_f32_e32 v7, 0xba800000, v4
	v_fmac_f32_e32 v18, 0xba800000, v4
	v_fmac_f32_e32 v8, 0xba800000, v4
	v_fmac_f32_e32 v19, 0xba800000, v4
	v_fmac_f32_e32 v9, 0xba800000, v4
	v_fmac_f32_e32 v20, 0xba800000, v4
	v_fmac_f32_e32 v10, 0xba800000, v4
	v_fmac_f32_e32 v21, 0xba800000, v4
	v_fmac_f32_e32 v11, 0xba800000, v4
	v_mul_f32_e32 v23, v13, v13
	v_fmac_f32_e32 v23, v14, v14
	v_fmac_f32_e32 v23, v15, v15
	v_fmac_f32_e32 v23, v5, v5
	v_fmac_f32_e32 v23, v16, v16
	v_fmac_f32_e32 v23, v6, v6
	v_fmac_f32_e32 v23, v17, v17
	v_fmac_f32_e32 v23, v7, v7
	v_fmac_f32_e32 v23, v18, v18
	v_fmac_f32_e32 v23, v8, v8
	v_fmac_f32_e32 v23, v19, v19
	v_fmac_f32_e32 v23, v9, v9
	v_fmac_f32_e32 v23, v20, v20
	v_fmac_f32_e32 v23, v10, v10
	v_fmac_f32_e32 v23, v21, v21
	v_fmac_f32_e32 v23, v11, v11
	s_nop 1
	v_add_f32_dpp v23, v23, v23 row_ror:8 row_mask:0xf bank_mask:0xf bound_ctrl:1
	s_nop 1
	v_add_f32_dpp v23, v23, v23 row_ror:4 row_mask:0xf bank_mask:0xf bound_ctrl:1
	s_nop 1
	v_add_f32_dpp v23, v23, v23 row_ror:2 row_mask:0xf bank_mask:0xf bound_ctrl:1
	s_nop 1
	v_add_f32_dpp v23, v23, v23 row_ror:1 row_mask:0xf bank_mask:0xf bound_ctrl:1
	v_mov_b32_e32 v22, v23
	s_nop 1
	v_permlane16_swap_b32_e32 v23, v22
	v_add_f32_e32 v23, v23, v22
	v_mov_b32_e32 v22, v23
	s_nop 1
	v_permlane32_swap_b32_e32 v23, v22
	v_add_f32_e32 v23, v23, v22
	s_and_saveexec_b64 s[12:13], s[6:7]
	v_mov_b32_e32 v5, v23
	v_fmamk_f32 v5, v5, 0x3a800000, v112
	v_mul_f32_e32 v6, 0x4f800000, v5
	v_cmp_gt_f32_e32 vcc, s67, v5
	v_mul_f32_e32 v4, 0x3a800000, v4
	s_nop 0
	v_cndmask_b32_e32 v5, v5, v6, vcc
	v_sqrt_f32_e32 v6, v5
	s_nop 0
	v_add_u32_e32 v7, -1, v6
	v_fma_f32 v9, -v7, v6, v5
	v_add_u32_e32 v8, 1, v6
	v_cmp_ge_f32_e64 s[8:9], 0, v9
	s_nop 1
	v_cndmask_b32_e64 v7, v6, v7, s[8:9]
	v_fma_f32 v6, -v8, v6, v5
	v_cmp_lt_f32_e64 s[8:9], 0, v6
	s_nop 1
	v_cndmask_b32_e64 v6, v7, v8, s[8:9]
	v_mul_f32_e32 v7, 0x37800000, v6
	v_cndmask_b32_e32 v6, v6, v7, vcc
	v_cmp_class_f32_e32 vcc, v5, v113
	s_nop 1
	v_cndmask_b32_e32 v5, v6, v5, vcc
	v_div_scale_f32 v6, s[8:9], v5, v5, 1.0
	v_rcp_f32_e32 v7, v6
	s_nop 0
	v_fma_f32 v8, -v6, v7, 1.0
	v_fmac_f32_e32 v7, v8, v7
	v_div_scale_f32 v8, vcc, 1.0, v5, 1.0
	v_mul_f32_e32 v9, v8, v7
	v_fma_f32 v10, -v6, v9, v8
	v_fmac_f32_e32 v9, v10, v7
	v_fma_f32 v6, -v6, v9, v8
	s_nop 1
	v_div_fmas_f32 v6, v6, v7, v9
	v_div_fixup_f32 v5, v6, v5, 1.0
	ds_write_b64 v62, v[4:5] offset:48
	s_or_b64 exec, exec, s[12:13]
	s_waitcnt vmcnt(16)
	v_mov_b32_e32 v4, v90
	v_mov_b32_e32 v5, v91
	v_mov_b32_e32 v6, v92
	v_mov_b32_e32 v7, v93
	v_mov_b32_e32 v8, v94
	v_mov_b32_e32 v9, v95
	v_mov_b32_e32 v10, v96
	v_mov_b32_e32 v11, v97
	v_lshlrev_b32_e32 v13, 16, v4
	v_and_b32_e32 v14, 0xffff0000, v4
	v_lshlrev_b32_e32 v15, 16, v5
	v_and_b32_e32 v5, 0xffff0000, v5
	v_lshlrev_b32_e32 v16, 16, v6
	v_and_b32_e32 v6, 0xffff0000, v6
	v_lshlrev_b32_e32 v17, 16, v7
	v_and_b32_e32 v7, 0xffff0000, v7
	v_lshlrev_b32_e32 v18, 16, v8
	v_and_b32_e32 v8, 0xffff0000, v8
	v_lshlrev_b32_e32 v19, 16, v9
	v_and_b32_e32 v9, 0xffff0000, v9
	v_lshlrev_b32_e32 v20, 16, v10
	v_and_b32_e32 v10, 0xffff0000, v10
	v_lshlrev_b32_e32 v21, 16, v11
	v_and_b32_e32 v11, 0xffff0000, v11
	v_add_f32_e32 v22, v13, v14
	v_add_f32_e32 v23, v15, v5
	v_add_f32_e32 v24, v16, v6
	v_add_f32_e32 v25, v17, v7
	v_add_f32_e32 v26, v18, v8
	v_add_f32_e32 v27, v19, v9
	v_add_f32_e32 v12, v20, v10
	v_add_f32_e32 v4, v21, v11
	v_add_f32_e32 v22, v22, v23
	v_add_f32_e32 v24, v24, v25
	v_add_f32_e32 v26, v26, v27
	v_add_f32_e32 v4, v12, v4
	v_add_f32_e32 v22, v22, v24
	v_add_f32_e32 v4, v26, v4
	v_add_f32_e32 v4, v22, v4
	s_nop 1
	v_add_f32_dpp v4, v4, v4 row_ror:8 row_mask:0xf bank_mask:0xf bound_ctrl:1
	s_nop 1
	v_add_f32_dpp v4, v4, v4 row_ror:4 row_mask:0xf bank_mask:0xf bound_ctrl:1
	s_nop 1
	v_add_f32_dpp v4, v4, v4 row_ror:2 row_mask:0xf bank_mask:0xf bound_ctrl:1
	s_nop 1
	v_add_f32_dpp v4, v4, v4 row_ror:1 row_mask:0xf bank_mask:0xf bound_ctrl:1
	v_mov_b32_e32 v22, v4
	s_nop 1
	v_permlane16_swap_b32_e32 v4, v22
	v_add_f32_e32 v4, v4, v22
	v_mov_b32_e32 v22, v4
	s_nop 1
	v_permlane32_swap_b32_e32 v4, v22
	v_add_f32_e32 v4, v4, v22
	v_fmac_f32_e32 v13, 0xba800000, v4
	v_fmac_f32_e32 v14, 0xba800000, v4
	v_fmac_f32_e32 v15, 0xba800000, v4
	v_fmac_f32_e32 v5, 0xba800000, v4
	v_fmac_f32_e32 v16, 0xba800000, v4
	v_fmac_f32_e32 v6, 0xba800000, v4
	v_fmac_f32_e32 v17, 0xba800000, v4
	v_fmac_f32_e32 v7, 0xba800000, v4
	v_fmac_f32_e32 v18, 0xba800000, v4
	v_fmac_f32_e32 v8, 0xba800000, v4
	v_fmac_f32_e32 v19, 0xba800000, v4
	v_fmac_f32_e32 v9, 0xba800000, v4
	v_fmac_f32_e32 v20, 0xba800000, v4
	v_fmac_f32_e32 v10, 0xba800000, v4
	v_fmac_f32_e32 v21, 0xba800000, v4
	v_fmac_f32_e32 v11, 0xba800000, v4
	v_mul_f32_e32 v23, v13, v13
	v_fmac_f32_e32 v23, v14, v14
	v_fmac_f32_e32 v23, v15, v15
	v_fmac_f32_e32 v23, v5, v5
	v_fmac_f32_e32 v23, v16, v16
	v_fmac_f32_e32 v23, v6, v6
	v_fmac_f32_e32 v23, v17, v17
	v_fmac_f32_e32 v23, v7, v7
	v_fmac_f32_e32 v23, v18, v18
	v_fmac_f32_e32 v23, v8, v8
	v_fmac_f32_e32 v23, v19, v19
	v_fmac_f32_e32 v23, v9, v9
	v_fmac_f32_e32 v23, v20, v20
	v_fmac_f32_e32 v23, v10, v10
	v_fmac_f32_e32 v23, v21, v21
	v_fmac_f32_e32 v23, v11, v11
	s_nop 1
	v_add_f32_dpp v23, v23, v23 row_ror:8 row_mask:0xf bank_mask:0xf bound_ctrl:1
	s_nop 1
	v_add_f32_dpp v23, v23, v23 row_ror:4 row_mask:0xf bank_mask:0xf bound_ctrl:1
	s_nop 1
	v_add_f32_dpp v23, v23, v23 row_ror:2 row_mask:0xf bank_mask:0xf bound_ctrl:1
	s_nop 1
	v_add_f32_dpp v23, v23, v23 row_ror:1 row_mask:0xf bank_mask:0xf bound_ctrl:1
	v_mov_b32_e32 v22, v23
	s_nop 1
	v_permlane16_swap_b32_e32 v23, v22
	v_add_f32_e32 v23, v23, v22
	v_mov_b32_e32 v22, v23
	s_nop 1
	v_permlane32_swap_b32_e32 v23, v22
	v_add_f32_e32 v23, v23, v22
	s_and_saveexec_b64 s[12:13], s[6:7]
	v_mov_b32_e32 v5, v23
	v_fmamk_f32 v5, v5, 0x3a800000, v112
	v_mul_f32_e32 v6, 0x4f800000, v5
	v_cmp_gt_f32_e32 vcc, s67, v5
	v_mul_f32_e32 v4, 0x3a800000, v4
	s_nop 0
	v_cndmask_b32_e32 v5, v5, v6, vcc
	v_sqrt_f32_e32 v6, v5
	s_nop 0
	v_add_u32_e32 v7, -1, v6
	v_fma_f32 v9, -v7, v6, v5
	v_add_u32_e32 v8, 1, v6
	v_cmp_ge_f32_e64 s[8:9], 0, v9
	s_nop 1
	v_cndmask_b32_e64 v7, v6, v7, s[8:9]
	v_fma_f32 v6, -v8, v6, v5
	v_cmp_lt_f32_e64 s[8:9], 0, v6
	s_nop 1
	v_cndmask_b32_e64 v6, v7, v8, s[8:9]
	v_mul_f32_e32 v7, 0x37800000, v6
	v_cndmask_b32_e32 v6, v6, v7, vcc
	v_cmp_class_f32_e32 vcc, v5, v113
	s_nop 1
	v_cndmask_b32_e32 v5, v6, v5, vcc
	v_div_scale_f32 v6, s[8:9], v5, v5, 1.0
	v_rcp_f32_e32 v7, v6
	s_nop 0
	v_fma_f32 v8, -v6, v7, 1.0
	v_fmac_f32_e32 v7, v8, v7
	v_div_scale_f32 v8, vcc, 1.0, v5, 1.0
	v_mul_f32_e32 v9, v8, v7
	v_fma_f32 v10, -v6, v9, v8
	v_fmac_f32_e32 v9, v10, v7
	v_fma_f32 v6, -v6, v9, v8
	s_nop 1
	v_div_fmas_f32 v6, v6, v7, v9
	v_div_fixup_f32 v5, v6, v5, 1.0
	ds_write_b64 v62, v[4:5] offset:56
	s_or_b64 exec, exec, s[12:13]
	s_waitcnt vmcnt(14)
	v_mov_b32_e32 v4, v98
	v_mov_b32_e32 v5, v99
	v_mov_b32_e32 v6, v100
	v_mov_b32_e32 v7, v101
	v_mov_b32_e32 v8, v102
	v_mov_b32_e32 v9, v103
	v_mov_b32_e32 v10, v104
	v_mov_b32_e32 v11, v105
	v_lshlrev_b32_e32 v13, 16, v4
	v_and_b32_e32 v14, 0xffff0000, v4
	v_lshlrev_b32_e32 v15, 16, v5
	v_and_b32_e32 v5, 0xffff0000, v5
	v_lshlrev_b32_e32 v16, 16, v6
	v_and_b32_e32 v6, 0xffff0000, v6
	v_lshlrev_b32_e32 v17, 16, v7
	v_and_b32_e32 v7, 0xffff0000, v7
	v_lshlrev_b32_e32 v18, 16, v8
	v_and_b32_e32 v8, 0xffff0000, v8
	v_lshlrev_b32_e32 v19, 16, v9
	v_and_b32_e32 v9, 0xffff0000, v9
	v_lshlrev_b32_e32 v20, 16, v10
	v_and_b32_e32 v10, 0xffff0000, v10
	v_lshlrev_b32_e32 v21, 16, v11
	v_and_b32_e32 v11, 0xffff0000, v11
	v_add_f32_e32 v22, v13, v14
	v_add_f32_e32 v23, v15, v5
	v_add_f32_e32 v24, v16, v6
	v_add_f32_e32 v25, v17, v7
	v_add_f32_e32 v26, v18, v8
	v_add_f32_e32 v27, v19, v9
	v_add_f32_e32 v12, v20, v10
	v_add_f32_e32 v4, v21, v11
	v_add_f32_e32 v22, v22, v23
	v_add_f32_e32 v24, v24, v25
	v_add_f32_e32 v26, v26, v27
	v_add_f32_e32 v4, v12, v4
	v_add_f32_e32 v22, v22, v24
	v_add_f32_e32 v4, v26, v4
	v_add_f32_e32 v4, v22, v4
	s_nop 1
	v_add_f32_dpp v4, v4, v4 row_ror:8 row_mask:0xf bank_mask:0xf bound_ctrl:1
	s_nop 1
	v_add_f32_dpp v4, v4, v4 row_ror:4 row_mask:0xf bank_mask:0xf bound_ctrl:1
	s_nop 1
	v_add_f32_dpp v4, v4, v4 row_ror:2 row_mask:0xf bank_mask:0xf bound_ctrl:1
	s_nop 1
	v_add_f32_dpp v4, v4, v4 row_ror:1 row_mask:0xf bank_mask:0xf bound_ctrl:1
	v_mov_b32_e32 v22, v4
	s_nop 1
	v_permlane16_swap_b32_e32 v4, v22
	v_add_f32_e32 v4, v4, v22
	v_mov_b32_e32 v22, v4
	s_nop 1
	v_permlane32_swap_b32_e32 v4, v22
	v_add_f32_e32 v4, v4, v22
	v_fmac_f32_e32 v13, 0xba800000, v4
	v_fmac_f32_e32 v14, 0xba800000, v4
	v_fmac_f32_e32 v15, 0xba800000, v4
	v_fmac_f32_e32 v5, 0xba800000, v4
	v_fmac_f32_e32 v16, 0xba800000, v4
	v_fmac_f32_e32 v6, 0xba800000, v4
	v_fmac_f32_e32 v17, 0xba800000, v4
	v_fmac_f32_e32 v7, 0xba800000, v4
	v_fmac_f32_e32 v18, 0xba800000, v4
	v_fmac_f32_e32 v8, 0xba800000, v4
	v_fmac_f32_e32 v19, 0xba800000, v4
	v_fmac_f32_e32 v9, 0xba800000, v4
	v_fmac_f32_e32 v20, 0xba800000, v4
	v_fmac_f32_e32 v10, 0xba800000, v4
	v_fmac_f32_e32 v21, 0xba800000, v4
	v_fmac_f32_e32 v11, 0xba800000, v4
	v_mul_f32_e32 v23, v13, v13
	v_fmac_f32_e32 v23, v14, v14
	v_fmac_f32_e32 v23, v15, v15
	v_fmac_f32_e32 v23, v5, v5
	v_fmac_f32_e32 v23, v16, v16
	v_fmac_f32_e32 v23, v6, v6
	v_fmac_f32_e32 v23, v17, v17
	v_fmac_f32_e32 v23, v7, v7
	v_fmac_f32_e32 v23, v18, v18
	v_fmac_f32_e32 v23, v8, v8
	v_fmac_f32_e32 v23, v19, v19
	v_fmac_f32_e32 v23, v9, v9
	v_fmac_f32_e32 v23, v20, v20
	v_fmac_f32_e32 v23, v10, v10
	v_fmac_f32_e32 v23, v21, v21
	v_fmac_f32_e32 v23, v11, v11
	s_nop 1
	v_add_f32_dpp v23, v23, v23 row_ror:8 row_mask:0xf bank_mask:0xf bound_ctrl:1
	s_nop 1
	v_add_f32_dpp v23, v23, v23 row_ror:4 row_mask:0xf bank_mask:0xf bound_ctrl:1
	s_nop 1
	v_add_f32_dpp v23, v23, v23 row_ror:2 row_mask:0xf bank_mask:0xf bound_ctrl:1
	s_nop 1
	v_add_f32_dpp v23, v23, v23 row_ror:1 row_mask:0xf bank_mask:0xf bound_ctrl:1
	v_mov_b32_e32 v22, v23
	s_nop 1
	v_permlane16_swap_b32_e32 v23, v22
	v_add_f32_e32 v23, v23, v22
	v_mov_b32_e32 v22, v23
	s_nop 1
	v_permlane32_swap_b32_e32 v23, v22
	v_add_f32_e32 v23, v23, v22
	s_and_saveexec_b64 s[12:13], s[6:7]
	v_mov_b32_e32 v5, v23
	v_fmamk_f32 v5, v5, 0x3a800000, v112
	v_mul_f32_e32 v6, 0x4f800000, v5
	v_cmp_gt_f32_e32 vcc, s67, v5
	v_mul_f32_e32 v4, 0x3a800000, v4
	s_nop 0
	v_cndmask_b32_e32 v5, v5, v6, vcc
	v_sqrt_f32_e32 v6, v5
	s_nop 0
	v_add_u32_e32 v7, -1, v6
	v_fma_f32 v9, -v7, v6, v5
	v_add_u32_e32 v8, 1, v6
	v_cmp_ge_f32_e64 s[8:9], 0, v9
	s_nop 1
	v_cndmask_b32_e64 v7, v6, v7, s[8:9]
	v_fma_f32 v6, -v8, v6, v5
	v_cmp_lt_f32_e64 s[8:9], 0, v6
	s_nop 1
	v_cndmask_b32_e64 v6, v7, v8, s[8:9]
	v_mul_f32_e32 v7, 0x37800000, v6
	v_cndmask_b32_e32 v6, v6, v7, vcc
	v_cmp_class_f32_e32 vcc, v5, v113
	s_nop 1
	v_cndmask_b32_e32 v5, v6, v5, vcc
	v_div_scale_f32 v6, s[8:9], v5, v5, 1.0
	v_rcp_f32_e32 v7, v6
	s_nop 0
	v_fma_f32 v8, -v6, v7, 1.0
	v_fmac_f32_e32 v7, v8, v7
	v_div_scale_f32 v8, vcc, 1.0, v5, 1.0
	v_mul_f32_e32 v9, v8, v7
	v_fma_f32 v10, -v6, v9, v8
	v_fmac_f32_e32 v9, v10, v7
	v_fma_f32 v6, -v6, v9, v8
	s_nop 1
	v_div_fmas_f32 v6, v6, v7, v9
	v_div_fixup_f32 v5, v6, v5, 1.0
	ds_write_b64 v62, v[4:5] offset:64
	s_or_b64 exec, exec, s[12:13]
	s_waitcnt vmcnt(12)
	v_mov_b32_e32 v4, v122
	v_mov_b32_e32 v5, v123
	v_mov_b32_e32 v6, v124
	v_mov_b32_e32 v7, v125
	v_mov_b32_e32 v8, v126
	v_mov_b32_e32 v9, v127
	v_mov_b32_e32 v10, v128
	v_mov_b32_e32 v11, v129
	v_lshlrev_b32_e32 v13, 16, v4
	v_and_b32_e32 v14, 0xffff0000, v4
	v_lshlrev_b32_e32 v15, 16, v5
	v_and_b32_e32 v5, 0xffff0000, v5
	v_lshlrev_b32_e32 v16, 16, v6
	v_and_b32_e32 v6, 0xffff0000, v6
	v_lshlrev_b32_e32 v17, 16, v7
	v_and_b32_e32 v7, 0xffff0000, v7
	v_lshlrev_b32_e32 v18, 16, v8
	v_and_b32_e32 v8, 0xffff0000, v8
	v_lshlrev_b32_e32 v19, 16, v9
	v_and_b32_e32 v9, 0xffff0000, v9
	v_lshlrev_b32_e32 v20, 16, v10
	v_and_b32_e32 v10, 0xffff0000, v10
	v_lshlrev_b32_e32 v21, 16, v11
	v_and_b32_e32 v11, 0xffff0000, v11
	v_add_f32_e32 v22, v13, v14
	v_add_f32_e32 v23, v15, v5
	v_add_f32_e32 v24, v16, v6
	v_add_f32_e32 v25, v17, v7
	v_add_f32_e32 v26, v18, v8
	v_add_f32_e32 v27, v19, v9
	v_add_f32_e32 v12, v20, v10
	v_add_f32_e32 v4, v21, v11
	v_add_f32_e32 v22, v22, v23
	v_add_f32_e32 v24, v24, v25
	v_add_f32_e32 v26, v26, v27
	v_add_f32_e32 v4, v12, v4
	v_add_f32_e32 v22, v22, v24
	v_add_f32_e32 v4, v26, v4
	v_add_f32_e32 v4, v22, v4
	s_nop 1
	v_add_f32_dpp v4, v4, v4 row_ror:8 row_mask:0xf bank_mask:0xf bound_ctrl:1
	s_nop 1
	v_add_f32_dpp v4, v4, v4 row_ror:4 row_mask:0xf bank_mask:0xf bound_ctrl:1
	s_nop 1
	v_add_f32_dpp v4, v4, v4 row_ror:2 row_mask:0xf bank_mask:0xf bound_ctrl:1
	s_nop 1
	v_add_f32_dpp v4, v4, v4 row_ror:1 row_mask:0xf bank_mask:0xf bound_ctrl:1
	v_mov_b32_e32 v22, v4
	s_nop 1
	v_permlane16_swap_b32_e32 v4, v22
	v_add_f32_e32 v4, v4, v22
	v_mov_b32_e32 v22, v4
	s_nop 1
	v_permlane32_swap_b32_e32 v4, v22
	v_add_f32_e32 v4, v4, v22
	v_fmac_f32_e32 v13, 0xba800000, v4
	v_fmac_f32_e32 v14, 0xba800000, v4
	v_fmac_f32_e32 v15, 0xba800000, v4
	v_fmac_f32_e32 v5, 0xba800000, v4
	v_fmac_f32_e32 v16, 0xba800000, v4
	v_fmac_f32_e32 v6, 0xba800000, v4
	v_fmac_f32_e32 v17, 0xba800000, v4
	v_fmac_f32_e32 v7, 0xba800000, v4
	v_fmac_f32_e32 v18, 0xba800000, v4
	v_fmac_f32_e32 v8, 0xba800000, v4
	v_fmac_f32_e32 v19, 0xba800000, v4
	v_fmac_f32_e32 v9, 0xba800000, v4
	v_fmac_f32_e32 v20, 0xba800000, v4
	v_fmac_f32_e32 v10, 0xba800000, v4
	v_fmac_f32_e32 v21, 0xba800000, v4
	v_fmac_f32_e32 v11, 0xba800000, v4
	v_mul_f32_e32 v23, v13, v13
	v_fmac_f32_e32 v23, v14, v14
	v_fmac_f32_e32 v23, v15, v15
	v_fmac_f32_e32 v23, v5, v5
	v_fmac_f32_e32 v23, v16, v16
	v_fmac_f32_e32 v23, v6, v6
	v_fmac_f32_e32 v23, v17, v17
	v_fmac_f32_e32 v23, v7, v7
	v_fmac_f32_e32 v23, v18, v18
	v_fmac_f32_e32 v23, v8, v8
	v_fmac_f32_e32 v23, v19, v19
	v_fmac_f32_e32 v23, v9, v9
	v_fmac_f32_e32 v23, v20, v20
	v_fmac_f32_e32 v23, v10, v10
	v_fmac_f32_e32 v23, v21, v21
	v_fmac_f32_e32 v23, v11, v11
	s_nop 1
	v_add_f32_dpp v23, v23, v23 row_ror:8 row_mask:0xf bank_mask:0xf bound_ctrl:1
	s_nop 1
	v_add_f32_dpp v23, v23, v23 row_ror:4 row_mask:0xf bank_mask:0xf bound_ctrl:1
	s_nop 1
	v_add_f32_dpp v23, v23, v23 row_ror:2 row_mask:0xf bank_mask:0xf bound_ctrl:1
	s_nop 1
	v_add_f32_dpp v23, v23, v23 row_ror:1 row_mask:0xf bank_mask:0xf bound_ctrl:1
	v_mov_b32_e32 v22, v23
	s_nop 1
	v_permlane16_swap_b32_e32 v23, v22
	v_add_f32_e32 v23, v23, v22
	v_mov_b32_e32 v22, v23
	s_nop 1
	v_permlane32_swap_b32_e32 v23, v22
	v_add_f32_e32 v23, v23, v22
	s_and_saveexec_b64 s[12:13], s[6:7]
	v_mov_b32_e32 v5, v23
	v_fmamk_f32 v5, v5, 0x3a800000, v112
	v_mul_f32_e32 v6, 0x4f800000, v5
	v_cmp_gt_f32_e32 vcc, s67, v5
	v_mul_f32_e32 v4, 0x3a800000, v4
	s_nop 0
	v_cndmask_b32_e32 v5, v5, v6, vcc
	v_sqrt_f32_e32 v6, v5
	s_nop 0
	v_add_u32_e32 v7, -1, v6
	v_fma_f32 v9, -v7, v6, v5
	v_add_u32_e32 v8, 1, v6
	v_cmp_ge_f32_e64 s[8:9], 0, v9
	s_nop 1
	v_cndmask_b32_e64 v7, v6, v7, s[8:9]
	v_fma_f32 v6, -v8, v6, v5
	v_cmp_lt_f32_e64 s[8:9], 0, v6
	s_nop 1
	v_cndmask_b32_e64 v6, v7, v8, s[8:9]
	v_mul_f32_e32 v7, 0x37800000, v6
	v_cndmask_b32_e32 v6, v6, v7, vcc
	v_cmp_class_f32_e32 vcc, v5, v113
	s_nop 1
	v_cndmask_b32_e32 v5, v6, v5, vcc
	v_div_scale_f32 v6, s[8:9], v5, v5, 1.0
	v_rcp_f32_e32 v7, v6
	s_nop 0
	v_fma_f32 v8, -v6, v7, 1.0
	v_fmac_f32_e32 v7, v8, v7
	v_div_scale_f32 v8, vcc, 1.0, v5, 1.0
	v_mul_f32_e32 v9, v8, v7
	v_fma_f32 v10, -v6, v9, v8
	v_fmac_f32_e32 v9, v10, v7
	v_fma_f32 v6, -v6, v9, v8
	s_nop 1
	v_div_fmas_f32 v6, v6, v7, v9
	v_div_fixup_f32 v5, v6, v5, 1.0
	ds_write_b64 v62, v[4:5] offset:72
	s_or_b64 exec, exec, s[12:13]
	s_waitcnt vmcnt(10)
	v_mov_b32_e32 v4, v130
	v_mov_b32_e32 v5, v131
	v_mov_b32_e32 v6, v132
	v_mov_b32_e32 v7, v133
	v_mov_b32_e32 v8, v134
	v_mov_b32_e32 v9, v135
	v_mov_b32_e32 v10, v136
	v_mov_b32_e32 v11, v137
	v_lshlrev_b32_e32 v13, 16, v4
	v_and_b32_e32 v14, 0xffff0000, v4
	v_lshlrev_b32_e32 v15, 16, v5
	v_and_b32_e32 v5, 0xffff0000, v5
	v_lshlrev_b32_e32 v16, 16, v6
	v_and_b32_e32 v6, 0xffff0000, v6
	v_lshlrev_b32_e32 v17, 16, v7
	v_and_b32_e32 v7, 0xffff0000, v7
	v_lshlrev_b32_e32 v18, 16, v8
	v_and_b32_e32 v8, 0xffff0000, v8
	v_lshlrev_b32_e32 v19, 16, v9
	v_and_b32_e32 v9, 0xffff0000, v9
	v_lshlrev_b32_e32 v20, 16, v10
	v_and_b32_e32 v10, 0xffff0000, v10
	v_lshlrev_b32_e32 v21, 16, v11
	v_and_b32_e32 v11, 0xffff0000, v11
	v_add_f32_e32 v22, v13, v14
	v_add_f32_e32 v23, v15, v5
	v_add_f32_e32 v24, v16, v6
	v_add_f32_e32 v25, v17, v7
	v_add_f32_e32 v26, v18, v8
	v_add_f32_e32 v27, v19, v9
	v_add_f32_e32 v12, v20, v10
	v_add_f32_e32 v4, v21, v11
	v_add_f32_e32 v22, v22, v23
	v_add_f32_e32 v24, v24, v25
	v_add_f32_e32 v26, v26, v27
	v_add_f32_e32 v4, v12, v4
	v_add_f32_e32 v22, v22, v24
	v_add_f32_e32 v4, v26, v4
	v_add_f32_e32 v4, v22, v4
	s_nop 1
	v_add_f32_dpp v4, v4, v4 row_ror:8 row_mask:0xf bank_mask:0xf bound_ctrl:1
	s_nop 1
	v_add_f32_dpp v4, v4, v4 row_ror:4 row_mask:0xf bank_mask:0xf bound_ctrl:1
	s_nop 1
	v_add_f32_dpp v4, v4, v4 row_ror:2 row_mask:0xf bank_mask:0xf bound_ctrl:1
	s_nop 1
	v_add_f32_dpp v4, v4, v4 row_ror:1 row_mask:0xf bank_mask:0xf bound_ctrl:1
	v_mov_b32_e32 v22, v4
	s_nop 1
	v_permlane16_swap_b32_e32 v4, v22
	v_add_f32_e32 v4, v4, v22
	v_mov_b32_e32 v22, v4
	s_nop 1
	v_permlane32_swap_b32_e32 v4, v22
	v_add_f32_e32 v4, v4, v22
	v_fmac_f32_e32 v13, 0xba800000, v4
	v_fmac_f32_e32 v14, 0xba800000, v4
	v_fmac_f32_e32 v15, 0xba800000, v4
	v_fmac_f32_e32 v5, 0xba800000, v4
	v_fmac_f32_e32 v16, 0xba800000, v4
	v_fmac_f32_e32 v6, 0xba800000, v4
	v_fmac_f32_e32 v17, 0xba800000, v4
	v_fmac_f32_e32 v7, 0xba800000, v4
	v_fmac_f32_e32 v18, 0xba800000, v4
	v_fmac_f32_e32 v8, 0xba800000, v4
	v_fmac_f32_e32 v19, 0xba800000, v4
	v_fmac_f32_e32 v9, 0xba800000, v4
	v_fmac_f32_e32 v20, 0xba800000, v4
	v_fmac_f32_e32 v10, 0xba800000, v4
	v_fmac_f32_e32 v21, 0xba800000, v4
	v_fmac_f32_e32 v11, 0xba800000, v4
	v_mul_f32_e32 v23, v13, v13
	v_fmac_f32_e32 v23, v14, v14
	v_fmac_f32_e32 v23, v15, v15
	v_fmac_f32_e32 v23, v5, v5
	v_fmac_f32_e32 v23, v16, v16
	v_fmac_f32_e32 v23, v6, v6
	v_fmac_f32_e32 v23, v17, v17
	v_fmac_f32_e32 v23, v7, v7
	v_fmac_f32_e32 v23, v18, v18
	v_fmac_f32_e32 v23, v8, v8
	v_fmac_f32_e32 v23, v19, v19
	v_fmac_f32_e32 v23, v9, v9
	v_fmac_f32_e32 v23, v20, v20
	v_fmac_f32_e32 v23, v10, v10
	v_fmac_f32_e32 v23, v21, v21
	v_fmac_f32_e32 v23, v11, v11
	s_nop 1
	v_add_f32_dpp v23, v23, v23 row_ror:8 row_mask:0xf bank_mask:0xf bound_ctrl:1
	s_nop 1
	v_add_f32_dpp v23, v23, v23 row_ror:4 row_mask:0xf bank_mask:0xf bound_ctrl:1
	s_nop 1
	v_add_f32_dpp v23, v23, v23 row_ror:2 row_mask:0xf bank_mask:0xf bound_ctrl:1
	s_nop 1
	v_add_f32_dpp v23, v23, v23 row_ror:1 row_mask:0xf bank_mask:0xf bound_ctrl:1
	v_mov_b32_e32 v22, v23
	s_nop 1
	v_permlane16_swap_b32_e32 v23, v22
	v_add_f32_e32 v23, v23, v22
	v_mov_b32_e32 v22, v23
	s_nop 1
	v_permlane32_swap_b32_e32 v23, v22
	v_add_f32_e32 v23, v23, v22
	s_and_saveexec_b64 s[12:13], s[6:7]
	v_mov_b32_e32 v5, v23
	v_fmamk_f32 v5, v5, 0x3a800000, v112
	v_mul_f32_e32 v6, 0x4f800000, v5
	v_cmp_gt_f32_e32 vcc, s67, v5
	v_mul_f32_e32 v4, 0x3a800000, v4
	s_nop 0
	v_cndmask_b32_e32 v5, v5, v6, vcc
	v_sqrt_f32_e32 v6, v5
	s_nop 0
	v_add_u32_e32 v7, -1, v6
	v_fma_f32 v9, -v7, v6, v5
	v_add_u32_e32 v8, 1, v6
	v_cmp_ge_f32_e64 s[8:9], 0, v9
	s_nop 1
	v_cndmask_b32_e64 v7, v6, v7, s[8:9]
	v_fma_f32 v6, -v8, v6, v5
	v_cmp_lt_f32_e64 s[8:9], 0, v6
	s_nop 1
	v_cndmask_b32_e64 v6, v7, v8, s[8:9]
	v_mul_f32_e32 v7, 0x37800000, v6
	v_cndmask_b32_e32 v6, v6, v7, vcc
	v_cmp_class_f32_e32 vcc, v5, v113
	s_nop 1
	v_cndmask_b32_e32 v5, v6, v5, vcc
	v_div_scale_f32 v6, s[8:9], v5, v5, 1.0
	v_rcp_f32_e32 v7, v6
	s_nop 0
	v_fma_f32 v8, -v6, v7, 1.0
	v_fmac_f32_e32 v7, v8, v7
	v_div_scale_f32 v8, vcc, 1.0, v5, 1.0
	v_mul_f32_e32 v9, v8, v7
	v_fma_f32 v10, -v6, v9, v8
	v_fmac_f32_e32 v9, v10, v7
	v_fma_f32 v6, -v6, v9, v8
	s_nop 1
	v_div_fmas_f32 v6, v6, v7, v9
	v_div_fixup_f32 v5, v6, v5, 1.0
	ds_write_b64 v62, v[4:5] offset:80
	s_or_b64 exec, exec, s[12:13]
	s_waitcnt vmcnt(8)
	v_mov_b32_e32 v4, v138
	v_mov_b32_e32 v5, v139
	v_mov_b32_e32 v6, v140
	v_mov_b32_e32 v7, v141
	v_mov_b32_e32 v8, v142
	v_mov_b32_e32 v9, v143
	v_mov_b32_e32 v10, v144
	v_mov_b32_e32 v11, v145
	v_lshlrev_b32_e32 v13, 16, v4
	v_and_b32_e32 v14, 0xffff0000, v4
	v_lshlrev_b32_e32 v15, 16, v5
	v_and_b32_e32 v5, 0xffff0000, v5
	v_lshlrev_b32_e32 v16, 16, v6
	v_and_b32_e32 v6, 0xffff0000, v6
	v_lshlrev_b32_e32 v17, 16, v7
	v_and_b32_e32 v7, 0xffff0000, v7
	v_lshlrev_b32_e32 v18, 16, v8
	v_and_b32_e32 v8, 0xffff0000, v8
	v_lshlrev_b32_e32 v19, 16, v9
	v_and_b32_e32 v9, 0xffff0000, v9
	v_lshlrev_b32_e32 v20, 16, v10
	v_and_b32_e32 v10, 0xffff0000, v10
	v_lshlrev_b32_e32 v21, 16, v11
	v_and_b32_e32 v11, 0xffff0000, v11
	v_add_f32_e32 v22, v13, v14
	v_add_f32_e32 v23, v15, v5
	v_add_f32_e32 v24, v16, v6
	v_add_f32_e32 v25, v17, v7
	v_add_f32_e32 v26, v18, v8
	v_add_f32_e32 v27, v19, v9
	v_add_f32_e32 v12, v20, v10
	v_add_f32_e32 v4, v21, v11
	v_add_f32_e32 v22, v22, v23
	v_add_f32_e32 v24, v24, v25
	v_add_f32_e32 v26, v26, v27
	v_add_f32_e32 v4, v12, v4
	v_add_f32_e32 v22, v22, v24
	v_add_f32_e32 v4, v26, v4
	v_add_f32_e32 v4, v22, v4
	s_nop 1
	v_add_f32_dpp v4, v4, v4 row_ror:8 row_mask:0xf bank_mask:0xf bound_ctrl:1
	s_nop 1
	v_add_f32_dpp v4, v4, v4 row_ror:4 row_mask:0xf bank_mask:0xf bound_ctrl:1
	s_nop 1
	v_add_f32_dpp v4, v4, v4 row_ror:2 row_mask:0xf bank_mask:0xf bound_ctrl:1
	s_nop 1
	v_add_f32_dpp v4, v4, v4 row_ror:1 row_mask:0xf bank_mask:0xf bound_ctrl:1
	v_mov_b32_e32 v22, v4
	s_nop 1
	v_permlane16_swap_b32_e32 v4, v22
	v_add_f32_e32 v4, v4, v22
	v_mov_b32_e32 v22, v4
	s_nop 1
	v_permlane32_swap_b32_e32 v4, v22
	v_add_f32_e32 v4, v4, v22
	v_fmac_f32_e32 v13, 0xba800000, v4
	v_fmac_f32_e32 v14, 0xba800000, v4
	v_fmac_f32_e32 v15, 0xba800000, v4
	v_fmac_f32_e32 v5, 0xba800000, v4
	v_fmac_f32_e32 v16, 0xba800000, v4
	v_fmac_f32_e32 v6, 0xba800000, v4
	v_fmac_f32_e32 v17, 0xba800000, v4
	v_fmac_f32_e32 v7, 0xba800000, v4
	v_fmac_f32_e32 v18, 0xba800000, v4
	v_fmac_f32_e32 v8, 0xba800000, v4
	v_fmac_f32_e32 v19, 0xba800000, v4
	v_fmac_f32_e32 v9, 0xba800000, v4
	v_fmac_f32_e32 v20, 0xba800000, v4
	v_fmac_f32_e32 v10, 0xba800000, v4
	v_fmac_f32_e32 v21, 0xba800000, v4
	v_fmac_f32_e32 v11, 0xba800000, v4
	v_mul_f32_e32 v23, v13, v13
	v_fmac_f32_e32 v23, v14, v14
	v_fmac_f32_e32 v23, v15, v15
	v_fmac_f32_e32 v23, v5, v5
	v_fmac_f32_e32 v23, v16, v16
	v_fmac_f32_e32 v23, v6, v6
	v_fmac_f32_e32 v23, v17, v17
	v_fmac_f32_e32 v23, v7, v7
	v_fmac_f32_e32 v23, v18, v18
	v_fmac_f32_e32 v23, v8, v8
	v_fmac_f32_e32 v23, v19, v19
	v_fmac_f32_e32 v23, v9, v9
	v_fmac_f32_e32 v23, v20, v20
	v_fmac_f32_e32 v23, v10, v10
	v_fmac_f32_e32 v23, v21, v21
	v_fmac_f32_e32 v23, v11, v11
	s_nop 1
	v_add_f32_dpp v23, v23, v23 row_ror:8 row_mask:0xf bank_mask:0xf bound_ctrl:1
	s_nop 1
	v_add_f32_dpp v23, v23, v23 row_ror:4 row_mask:0xf bank_mask:0xf bound_ctrl:1
	s_nop 1
	v_add_f32_dpp v23, v23, v23 row_ror:2 row_mask:0xf bank_mask:0xf bound_ctrl:1
	s_nop 1
	v_add_f32_dpp v23, v23, v23 row_ror:1 row_mask:0xf bank_mask:0xf bound_ctrl:1
	v_mov_b32_e32 v22, v23
	s_nop 1
	v_permlane16_swap_b32_e32 v23, v22
	v_add_f32_e32 v23, v23, v22
	v_mov_b32_e32 v22, v23
	s_nop 1
	v_permlane32_swap_b32_e32 v23, v22
	v_add_f32_e32 v23, v23, v22
	s_and_saveexec_b64 s[12:13], s[6:7]
	v_mov_b32_e32 v5, v23
	v_fmamk_f32 v5, v5, 0x3a800000, v112
	v_mul_f32_e32 v6, 0x4f800000, v5
	v_cmp_gt_f32_e32 vcc, s67, v5
	v_mul_f32_e32 v4, 0x3a800000, v4
	s_nop 0
	v_cndmask_b32_e32 v5, v5, v6, vcc
	v_sqrt_f32_e32 v6, v5
	s_nop 0
	v_add_u32_e32 v7, -1, v6
	v_fma_f32 v9, -v7, v6, v5
	v_add_u32_e32 v8, 1, v6
	v_cmp_ge_f32_e64 s[8:9], 0, v9
	s_nop 1
	v_cndmask_b32_e64 v7, v6, v7, s[8:9]
	v_fma_f32 v6, -v8, v6, v5
	v_cmp_lt_f32_e64 s[8:9], 0, v6
	s_nop 1
	v_cndmask_b32_e64 v6, v7, v8, s[8:9]
	v_mul_f32_e32 v7, 0x37800000, v6
	v_cndmask_b32_e32 v6, v6, v7, vcc
	v_cmp_class_f32_e32 vcc, v5, v113
	s_nop 1
	v_cndmask_b32_e32 v5, v6, v5, vcc
	v_div_scale_f32 v6, s[8:9], v5, v5, 1.0
	v_rcp_f32_e32 v7, v6
	s_nop 0
	v_fma_f32 v8, -v6, v7, 1.0
	v_fmac_f32_e32 v7, v8, v7
	v_div_scale_f32 v8, vcc, 1.0, v5, 1.0
	v_mul_f32_e32 v9, v8, v7
	v_fma_f32 v10, -v6, v9, v8
	v_fmac_f32_e32 v9, v10, v7
	v_fma_f32 v6, -v6, v9, v8
	s_nop 1
	v_div_fmas_f32 v6, v6, v7, v9
	v_div_fixup_f32 v5, v6, v5, 1.0
	ds_write_b64 v62, v[4:5] offset:88
	s_or_b64 exec, exec, s[12:13]
	s_waitcnt vmcnt(6)
	v_mov_b32_e32 v4, v146
	v_mov_b32_e32 v5, v147
	v_mov_b32_e32 v6, v148
	v_mov_b32_e32 v7, v149
	v_mov_b32_e32 v8, v150
	v_mov_b32_e32 v9, v151
	v_mov_b32_e32 v10, v152
	v_mov_b32_e32 v11, v153
	v_lshlrev_b32_e32 v13, 16, v4
	v_and_b32_e32 v14, 0xffff0000, v4
	v_lshlrev_b32_e32 v15, 16, v5
	v_and_b32_e32 v5, 0xffff0000, v5
	v_lshlrev_b32_e32 v16, 16, v6
	v_and_b32_e32 v6, 0xffff0000, v6
	v_lshlrev_b32_e32 v17, 16, v7
	v_and_b32_e32 v7, 0xffff0000, v7
	v_lshlrev_b32_e32 v18, 16, v8
	v_and_b32_e32 v8, 0xffff0000, v8
	v_lshlrev_b32_e32 v19, 16, v9
	v_and_b32_e32 v9, 0xffff0000, v9
	v_lshlrev_b32_e32 v20, 16, v10
	v_and_b32_e32 v10, 0xffff0000, v10
	v_lshlrev_b32_e32 v21, 16, v11
	v_and_b32_e32 v11, 0xffff0000, v11
	v_add_f32_e32 v22, v13, v14
	v_add_f32_e32 v23, v15, v5
	v_add_f32_e32 v24, v16, v6
	v_add_f32_e32 v25, v17, v7
	v_add_f32_e32 v26, v18, v8
	v_add_f32_e32 v27, v19, v9
	v_add_f32_e32 v12, v20, v10
	v_add_f32_e32 v4, v21, v11
	v_add_f32_e32 v22, v22, v23
	v_add_f32_e32 v24, v24, v25
	v_add_f32_e32 v26, v26, v27
	v_add_f32_e32 v4, v12, v4
	v_add_f32_e32 v22, v22, v24
	v_add_f32_e32 v4, v26, v4
	v_add_f32_e32 v4, v22, v4
	s_nop 1
	v_add_f32_dpp v4, v4, v4 row_ror:8 row_mask:0xf bank_mask:0xf bound_ctrl:1
	s_nop 1
	v_add_f32_dpp v4, v4, v4 row_ror:4 row_mask:0xf bank_mask:0xf bound_ctrl:1
	s_nop 1
	v_add_f32_dpp v4, v4, v4 row_ror:2 row_mask:0xf bank_mask:0xf bound_ctrl:1
	s_nop 1
	v_add_f32_dpp v4, v4, v4 row_ror:1 row_mask:0xf bank_mask:0xf bound_ctrl:1
	v_mov_b32_e32 v22, v4
	s_nop 1
	v_permlane16_swap_b32_e32 v4, v22
	v_add_f32_e32 v4, v4, v22
	v_mov_b32_e32 v22, v4
	s_nop 1
	v_permlane32_swap_b32_e32 v4, v22
	v_add_f32_e32 v4, v4, v22
	v_fmac_f32_e32 v13, 0xba800000, v4
	v_fmac_f32_e32 v14, 0xba800000, v4
	v_fmac_f32_e32 v15, 0xba800000, v4
	v_fmac_f32_e32 v5, 0xba800000, v4
	v_fmac_f32_e32 v16, 0xba800000, v4
	v_fmac_f32_e32 v6, 0xba800000, v4
	v_fmac_f32_e32 v17, 0xba800000, v4
	v_fmac_f32_e32 v7, 0xba800000, v4
	v_fmac_f32_e32 v18, 0xba800000, v4
	v_fmac_f32_e32 v8, 0xba800000, v4
	v_fmac_f32_e32 v19, 0xba800000, v4
	v_fmac_f32_e32 v9, 0xba800000, v4
	v_fmac_f32_e32 v20, 0xba800000, v4
	v_fmac_f32_e32 v10, 0xba800000, v4
	v_fmac_f32_e32 v21, 0xba800000, v4
	v_fmac_f32_e32 v11, 0xba800000, v4
	v_mul_f32_e32 v23, v13, v13
	v_fmac_f32_e32 v23, v14, v14
	v_fmac_f32_e32 v23, v15, v15
	v_fmac_f32_e32 v23, v5, v5
	v_fmac_f32_e32 v23, v16, v16
	v_fmac_f32_e32 v23, v6, v6
	v_fmac_f32_e32 v23, v17, v17
	v_fmac_f32_e32 v23, v7, v7
	v_fmac_f32_e32 v23, v18, v18
	v_fmac_f32_e32 v23, v8, v8
	v_fmac_f32_e32 v23, v19, v19
	v_fmac_f32_e32 v23, v9, v9
	v_fmac_f32_e32 v23, v20, v20
	v_fmac_f32_e32 v23, v10, v10
	v_fmac_f32_e32 v23, v21, v21
	v_fmac_f32_e32 v23, v11, v11
	s_nop 1
	v_add_f32_dpp v23, v23, v23 row_ror:8 row_mask:0xf bank_mask:0xf bound_ctrl:1
	s_nop 1
	v_add_f32_dpp v23, v23, v23 row_ror:4 row_mask:0xf bank_mask:0xf bound_ctrl:1
	s_nop 1
	v_add_f32_dpp v23, v23, v23 row_ror:2 row_mask:0xf bank_mask:0xf bound_ctrl:1
	s_nop 1
	v_add_f32_dpp v23, v23, v23 row_ror:1 row_mask:0xf bank_mask:0xf bound_ctrl:1
	v_mov_b32_e32 v22, v23
	s_nop 1
	v_permlane16_swap_b32_e32 v23, v22
	v_add_f32_e32 v23, v23, v22
	v_mov_b32_e32 v22, v23
	s_nop 1
	v_permlane32_swap_b32_e32 v23, v22
	v_add_f32_e32 v23, v23, v22
	s_and_saveexec_b64 s[12:13], s[6:7]
	v_mov_b32_e32 v5, v23
	v_fmamk_f32 v5, v5, 0x3a800000, v112
	v_mul_f32_e32 v6, 0x4f800000, v5
	v_cmp_gt_f32_e32 vcc, s67, v5
	v_mul_f32_e32 v4, 0x3a800000, v4
	s_nop 0
	v_cndmask_b32_e32 v5, v5, v6, vcc
	v_sqrt_f32_e32 v6, v5
	s_nop 0
	v_add_u32_e32 v7, -1, v6
	v_fma_f32 v9, -v7, v6, v5
	v_add_u32_e32 v8, 1, v6
	v_cmp_ge_f32_e64 s[8:9], 0, v9
	s_nop 1
	v_cndmask_b32_e64 v7, v6, v7, s[8:9]
	v_fma_f32 v6, -v8, v6, v5
	v_cmp_lt_f32_e64 s[8:9], 0, v6
	s_nop 1
	v_cndmask_b32_e64 v6, v7, v8, s[8:9]
	v_mul_f32_e32 v7, 0x37800000, v6
	v_cndmask_b32_e32 v6, v6, v7, vcc
	v_cmp_class_f32_e32 vcc, v5, v113
	s_nop 1
	v_cndmask_b32_e32 v5, v6, v5, vcc
	v_div_scale_f32 v6, s[8:9], v5, v5, 1.0
	v_rcp_f32_e32 v7, v6
	s_nop 0
	v_fma_f32 v8, -v6, v7, 1.0
	v_fmac_f32_e32 v7, v8, v7
	v_div_scale_f32 v8, vcc, 1.0, v5, 1.0
	v_mul_f32_e32 v9, v8, v7
	v_fma_f32 v10, -v6, v9, v8
	v_fmac_f32_e32 v9, v10, v7
	v_fma_f32 v6, -v6, v9, v8
	s_nop 1
	v_div_fmas_f32 v6, v6, v7, v9
	v_div_fixup_f32 v5, v6, v5, 1.0
	ds_write_b64 v62, v[4:5] offset:96
	s_or_b64 exec, exec, s[12:13]
	s_waitcnt vmcnt(4)
	v_mov_b32_e32 v4, v154
	v_mov_b32_e32 v5, v155
	v_mov_b32_e32 v6, v156
	v_mov_b32_e32 v7, v157
	v_mov_b32_e32 v8, v158
	v_mov_b32_e32 v9, v159
	v_mov_b32_e32 v10, v160
	v_mov_b32_e32 v11, v161
	v_lshlrev_b32_e32 v13, 16, v4
	v_and_b32_e32 v14, 0xffff0000, v4
	v_lshlrev_b32_e32 v15, 16, v5
	v_and_b32_e32 v5, 0xffff0000, v5
	v_lshlrev_b32_e32 v16, 16, v6
	v_and_b32_e32 v6, 0xffff0000, v6
	v_lshlrev_b32_e32 v17, 16, v7
	v_and_b32_e32 v7, 0xffff0000, v7
	v_lshlrev_b32_e32 v18, 16, v8
	v_and_b32_e32 v8, 0xffff0000, v8
	v_lshlrev_b32_e32 v19, 16, v9
	v_and_b32_e32 v9, 0xffff0000, v9
	v_lshlrev_b32_e32 v20, 16, v10
	v_and_b32_e32 v10, 0xffff0000, v10
	v_lshlrev_b32_e32 v21, 16, v11
	v_and_b32_e32 v11, 0xffff0000, v11
	v_add_f32_e32 v22, v13, v14
	v_add_f32_e32 v23, v15, v5
	v_add_f32_e32 v24, v16, v6
	v_add_f32_e32 v25, v17, v7
	v_add_f32_e32 v26, v18, v8
	v_add_f32_e32 v27, v19, v9
	v_add_f32_e32 v12, v20, v10
	v_add_f32_e32 v4, v21, v11
	v_add_f32_e32 v22, v22, v23
	v_add_f32_e32 v24, v24, v25
	v_add_f32_e32 v26, v26, v27
	v_add_f32_e32 v4, v12, v4
	v_add_f32_e32 v22, v22, v24
	v_add_f32_e32 v4, v26, v4
	v_add_f32_e32 v4, v22, v4
	s_nop 1
	v_add_f32_dpp v4, v4, v4 row_ror:8 row_mask:0xf bank_mask:0xf bound_ctrl:1
	s_nop 1
	v_add_f32_dpp v4, v4, v4 row_ror:4 row_mask:0xf bank_mask:0xf bound_ctrl:1
	s_nop 1
	v_add_f32_dpp v4, v4, v4 row_ror:2 row_mask:0xf bank_mask:0xf bound_ctrl:1
	s_nop 1
	v_add_f32_dpp v4, v4, v4 row_ror:1 row_mask:0xf bank_mask:0xf bound_ctrl:1
	v_mov_b32_e32 v22, v4
	s_nop 1
	v_permlane16_swap_b32_e32 v4, v22
	v_add_f32_e32 v4, v4, v22
	v_mov_b32_e32 v22, v4
	s_nop 1
	v_permlane32_swap_b32_e32 v4, v22
	v_add_f32_e32 v4, v4, v22
	v_fmac_f32_e32 v13, 0xba800000, v4
	v_fmac_f32_e32 v14, 0xba800000, v4
	v_fmac_f32_e32 v15, 0xba800000, v4
	v_fmac_f32_e32 v5, 0xba800000, v4
	v_fmac_f32_e32 v16, 0xba800000, v4
	v_fmac_f32_e32 v6, 0xba800000, v4
	v_fmac_f32_e32 v17, 0xba800000, v4
	v_fmac_f32_e32 v7, 0xba800000, v4
	v_fmac_f32_e32 v18, 0xba800000, v4
	v_fmac_f32_e32 v8, 0xba800000, v4
	v_fmac_f32_e32 v19, 0xba800000, v4
	v_fmac_f32_e32 v9, 0xba800000, v4
	v_fmac_f32_e32 v20, 0xba800000, v4
	v_fmac_f32_e32 v10, 0xba800000, v4
	v_fmac_f32_e32 v21, 0xba800000, v4
	v_fmac_f32_e32 v11, 0xba800000, v4
	v_mul_f32_e32 v23, v13, v13
	v_fmac_f32_e32 v23, v14, v14
	v_fmac_f32_e32 v23, v15, v15
	v_fmac_f32_e32 v23, v5, v5
	v_fmac_f32_e32 v23, v16, v16
	v_fmac_f32_e32 v23, v6, v6
	v_fmac_f32_e32 v23, v17, v17
	v_fmac_f32_e32 v23, v7, v7
	v_fmac_f32_e32 v23, v18, v18
	v_fmac_f32_e32 v23, v8, v8
	v_fmac_f32_e32 v23, v19, v19
	v_fmac_f32_e32 v23, v9, v9
	v_fmac_f32_e32 v23, v20, v20
	v_fmac_f32_e32 v23, v10, v10
	v_fmac_f32_e32 v23, v21, v21
	v_fmac_f32_e32 v23, v11, v11
	s_nop 1
	v_add_f32_dpp v23, v23, v23 row_ror:8 row_mask:0xf bank_mask:0xf bound_ctrl:1
	s_nop 1
	v_add_f32_dpp v23, v23, v23 row_ror:4 row_mask:0xf bank_mask:0xf bound_ctrl:1
	s_nop 1
	v_add_f32_dpp v23, v23, v23 row_ror:2 row_mask:0xf bank_mask:0xf bound_ctrl:1
	s_nop 1
	v_add_f32_dpp v23, v23, v23 row_ror:1 row_mask:0xf bank_mask:0xf bound_ctrl:1
	v_mov_b32_e32 v22, v23
	s_nop 1
	v_permlane16_swap_b32_e32 v23, v22
	v_add_f32_e32 v23, v23, v22
	v_mov_b32_e32 v22, v23
	s_nop 1
	v_permlane32_swap_b32_e32 v23, v22
	v_add_f32_e32 v23, v23, v22
	s_and_saveexec_b64 s[12:13], s[6:7]
	v_mov_b32_e32 v5, v23
	v_fmamk_f32 v5, v5, 0x3a800000, v112
	v_mul_f32_e32 v6, 0x4f800000, v5
	v_cmp_gt_f32_e32 vcc, s67, v5
	v_mul_f32_e32 v4, 0x3a800000, v4
	s_nop 0
	v_cndmask_b32_e32 v5, v5, v6, vcc
	v_sqrt_f32_e32 v6, v5
	s_nop 0
	v_add_u32_e32 v7, -1, v6
	v_fma_f32 v9, -v7, v6, v5
	v_add_u32_e32 v8, 1, v6
	v_cmp_ge_f32_e64 s[8:9], 0, v9
	s_nop 1
	v_cndmask_b32_e64 v7, v6, v7, s[8:9]
	v_fma_f32 v6, -v8, v6, v5
	v_cmp_lt_f32_e64 s[8:9], 0, v6
	s_nop 1
	v_cndmask_b32_e64 v6, v7, v8, s[8:9]
	v_mul_f32_e32 v7, 0x37800000, v6
	v_cndmask_b32_e32 v6, v6, v7, vcc
	v_cmp_class_f32_e32 vcc, v5, v113
	s_nop 1
	v_cndmask_b32_e32 v5, v6, v5, vcc
	v_div_scale_f32 v6, s[8:9], v5, v5, 1.0
	v_rcp_f32_e32 v7, v6
	s_nop 0
	v_fma_f32 v8, -v6, v7, 1.0
	v_fmac_f32_e32 v7, v8, v7
	v_div_scale_f32 v8, vcc, 1.0, v5, 1.0
	v_mul_f32_e32 v9, v8, v7
	v_fma_f32 v10, -v6, v9, v8
	v_fmac_f32_e32 v9, v10, v7
	v_fma_f32 v6, -v6, v9, v8
	s_nop 1
	v_div_fmas_f32 v6, v6, v7, v9
	v_div_fixup_f32 v5, v6, v5, 1.0
	ds_write_b64 v62, v[4:5] offset:104
	s_or_b64 exec, exec, s[12:13]
	s_waitcnt vmcnt(2)
	v_mov_b32_e32 v4, v162
	v_mov_b32_e32 v5, v163
	v_mov_b32_e32 v6, v164
	v_mov_b32_e32 v7, v165
	v_mov_b32_e32 v8, v166
	v_mov_b32_e32 v9, v167
	v_mov_b32_e32 v10, v168
	v_mov_b32_e32 v11, v169
	v_lshlrev_b32_e32 v13, 16, v4
	v_and_b32_e32 v14, 0xffff0000, v4
	v_lshlrev_b32_e32 v15, 16, v5
	v_and_b32_e32 v5, 0xffff0000, v5
	v_lshlrev_b32_e32 v16, 16, v6
	v_and_b32_e32 v6, 0xffff0000, v6
	v_lshlrev_b32_e32 v17, 16, v7
	v_and_b32_e32 v7, 0xffff0000, v7
	v_lshlrev_b32_e32 v18, 16, v8
	v_and_b32_e32 v8, 0xffff0000, v8
	v_lshlrev_b32_e32 v19, 16, v9
	v_and_b32_e32 v9, 0xffff0000, v9
	v_lshlrev_b32_e32 v20, 16, v10
	v_and_b32_e32 v10, 0xffff0000, v10
	v_lshlrev_b32_e32 v21, 16, v11
	v_and_b32_e32 v11, 0xffff0000, v11
	v_add_f32_e32 v22, v13, v14
	v_add_f32_e32 v23, v15, v5
	v_add_f32_e32 v24, v16, v6
	v_add_f32_e32 v25, v17, v7
	v_add_f32_e32 v26, v18, v8
	v_add_f32_e32 v27, v19, v9
	v_add_f32_e32 v12, v20, v10
	v_add_f32_e32 v4, v21, v11
	v_add_f32_e32 v22, v22, v23
	v_add_f32_e32 v24, v24, v25
	v_add_f32_e32 v26, v26, v27
	v_add_f32_e32 v4, v12, v4
	v_add_f32_e32 v22, v22, v24
	v_add_f32_e32 v4, v26, v4
	v_add_f32_e32 v4, v22, v4
	s_nop 1
	v_add_f32_dpp v4, v4, v4 row_ror:8 row_mask:0xf bank_mask:0xf bound_ctrl:1
	s_nop 1
	v_add_f32_dpp v4, v4, v4 row_ror:4 row_mask:0xf bank_mask:0xf bound_ctrl:1
	s_nop 1
	v_add_f32_dpp v4, v4, v4 row_ror:2 row_mask:0xf bank_mask:0xf bound_ctrl:1
	s_nop 1
	v_add_f32_dpp v4, v4, v4 row_ror:1 row_mask:0xf bank_mask:0xf bound_ctrl:1
	v_mov_b32_e32 v22, v4
	s_nop 1
	v_permlane16_swap_b32_e32 v4, v22
	v_add_f32_e32 v4, v4, v22
	v_mov_b32_e32 v22, v4
	s_nop 1
	v_permlane32_swap_b32_e32 v4, v22
	v_add_f32_e32 v4, v4, v22
	v_fmac_f32_e32 v13, 0xba800000, v4
	v_fmac_f32_e32 v14, 0xba800000, v4
	v_fmac_f32_e32 v15, 0xba800000, v4
	v_fmac_f32_e32 v5, 0xba800000, v4
	v_fmac_f32_e32 v16, 0xba800000, v4
	v_fmac_f32_e32 v6, 0xba800000, v4
	v_fmac_f32_e32 v17, 0xba800000, v4
	v_fmac_f32_e32 v7, 0xba800000, v4
	v_fmac_f32_e32 v18, 0xba800000, v4
	v_fmac_f32_e32 v8, 0xba800000, v4
	v_fmac_f32_e32 v19, 0xba800000, v4
	v_fmac_f32_e32 v9, 0xba800000, v4
	v_fmac_f32_e32 v20, 0xba800000, v4
	v_fmac_f32_e32 v10, 0xba800000, v4
	v_fmac_f32_e32 v21, 0xba800000, v4
	v_fmac_f32_e32 v11, 0xba800000, v4
	v_mul_f32_e32 v23, v13, v13
	v_fmac_f32_e32 v23, v14, v14
	v_fmac_f32_e32 v23, v15, v15
	v_fmac_f32_e32 v23, v5, v5
	v_fmac_f32_e32 v23, v16, v16
	v_fmac_f32_e32 v23, v6, v6
	v_fmac_f32_e32 v23, v17, v17
	v_fmac_f32_e32 v23, v7, v7
	v_fmac_f32_e32 v23, v18, v18
	v_fmac_f32_e32 v23, v8, v8
	v_fmac_f32_e32 v23, v19, v19
	v_fmac_f32_e32 v23, v9, v9
	v_fmac_f32_e32 v23, v20, v20
	v_fmac_f32_e32 v23, v10, v10
	v_fmac_f32_e32 v23, v21, v21
	v_fmac_f32_e32 v23, v11, v11
	s_nop 1
	v_add_f32_dpp v23, v23, v23 row_ror:8 row_mask:0xf bank_mask:0xf bound_ctrl:1
	s_nop 1
	v_add_f32_dpp v23, v23, v23 row_ror:4 row_mask:0xf bank_mask:0xf bound_ctrl:1
	s_nop 1
	v_add_f32_dpp v23, v23, v23 row_ror:2 row_mask:0xf bank_mask:0xf bound_ctrl:1
	s_nop 1
	v_add_f32_dpp v23, v23, v23 row_ror:1 row_mask:0xf bank_mask:0xf bound_ctrl:1
	v_mov_b32_e32 v22, v23
	s_nop 1
	v_permlane16_swap_b32_e32 v23, v22
	v_add_f32_e32 v23, v23, v22
	v_mov_b32_e32 v22, v23
	s_nop 1
	v_permlane32_swap_b32_e32 v23, v22
	v_add_f32_e32 v23, v23, v22
	s_and_saveexec_b64 s[12:13], s[6:7]
	v_mov_b32_e32 v5, v23
	v_fmamk_f32 v5, v5, 0x3a800000, v112
	v_mul_f32_e32 v6, 0x4f800000, v5
	v_cmp_gt_f32_e32 vcc, s67, v5
	v_mul_f32_e32 v4, 0x3a800000, v4
	s_nop 0
	v_cndmask_b32_e32 v5, v5, v6, vcc
	v_sqrt_f32_e32 v6, v5
	s_nop 0
	v_add_u32_e32 v7, -1, v6
	v_fma_f32 v9, -v7, v6, v5
	v_add_u32_e32 v8, 1, v6
	v_cmp_ge_f32_e64 s[8:9], 0, v9
	s_nop 1
	v_cndmask_b32_e64 v7, v6, v7, s[8:9]
	v_fma_f32 v6, -v8, v6, v5
	v_cmp_lt_f32_e64 s[8:9], 0, v6
	s_nop 1
	v_cndmask_b32_e64 v6, v7, v8, s[8:9]
	v_mul_f32_e32 v7, 0x37800000, v6
	v_cndmask_b32_e32 v6, v6, v7, vcc
	v_cmp_class_f32_e32 vcc, v5, v113
	s_nop 1
	v_cndmask_b32_e32 v5, v6, v5, vcc
	v_div_scale_f32 v6, s[8:9], v5, v5, 1.0
	v_rcp_f32_e32 v7, v6
	s_nop 0
	v_fma_f32 v8, -v6, v7, 1.0
	v_fmac_f32_e32 v7, v8, v7
	v_div_scale_f32 v8, vcc, 1.0, v5, 1.0
	v_mul_f32_e32 v9, v8, v7
	v_fma_f32 v10, -v6, v9, v8
	v_fmac_f32_e32 v9, v10, v7
	v_fma_f32 v6, -v6, v9, v8
	s_nop 1
	v_div_fmas_f32 v6, v6, v7, v9
	v_div_fixup_f32 v5, v6, v5, 1.0
	ds_write_b64 v62, v[4:5] offset:112
	s_or_b64 exec, exec, s[12:13]
	s_waitcnt vmcnt(0)
	v_mov_b32_e32 v4, v170
	v_mov_b32_e32 v5, v171
	v_mov_b32_e32 v6, v172
	v_mov_b32_e32 v7, v173
	v_mov_b32_e32 v8, v174
	v_mov_b32_e32 v9, v175
	v_mov_b32_e32 v10, v176
	v_mov_b32_e32 v11, v177
	v_lshlrev_b32_e32 v13, 16, v4
	v_and_b32_e32 v14, 0xffff0000, v4
	v_lshlrev_b32_e32 v15, 16, v5
	v_and_b32_e32 v5, 0xffff0000, v5
	v_lshlrev_b32_e32 v16, 16, v6
	v_and_b32_e32 v6, 0xffff0000, v6
	v_lshlrev_b32_e32 v17, 16, v7
	v_and_b32_e32 v7, 0xffff0000, v7
	v_lshlrev_b32_e32 v18, 16, v8
	v_and_b32_e32 v8, 0xffff0000, v8
	v_lshlrev_b32_e32 v19, 16, v9
	v_and_b32_e32 v9, 0xffff0000, v9
	v_lshlrev_b32_e32 v20, 16, v10
	v_and_b32_e32 v10, 0xffff0000, v10
	v_lshlrev_b32_e32 v21, 16, v11
	v_and_b32_e32 v11, 0xffff0000, v11
	v_add_f32_e32 v22, v13, v14
	v_add_f32_e32 v23, v15, v5
	v_add_f32_e32 v24, v16, v6
	v_add_f32_e32 v25, v17, v7
	v_add_f32_e32 v26, v18, v8
	v_add_f32_e32 v27, v19, v9
	v_add_f32_e32 v12, v20, v10
	v_add_f32_e32 v4, v21, v11
	v_add_f32_e32 v22, v22, v23
	v_add_f32_e32 v24, v24, v25
	v_add_f32_e32 v26, v26, v27
	v_add_f32_e32 v4, v12, v4
	v_add_f32_e32 v22, v22, v24
	v_add_f32_e32 v4, v26, v4
	v_add_f32_e32 v4, v22, v4
	s_nop 1
	v_add_f32_dpp v4, v4, v4 row_ror:8 row_mask:0xf bank_mask:0xf bound_ctrl:1
	s_nop 1
	v_add_f32_dpp v4, v4, v4 row_ror:4 row_mask:0xf bank_mask:0xf bound_ctrl:1
	s_nop 1
	v_add_f32_dpp v4, v4, v4 row_ror:2 row_mask:0xf bank_mask:0xf bound_ctrl:1
	s_nop 1
	v_add_f32_dpp v4, v4, v4 row_ror:1 row_mask:0xf bank_mask:0xf bound_ctrl:1
	v_mov_b32_e32 v22, v4
	s_nop 1
	v_permlane16_swap_b32_e32 v4, v22
	v_add_f32_e32 v4, v4, v22
	v_mov_b32_e32 v22, v4
	s_nop 1
	v_permlane32_swap_b32_e32 v4, v22
	v_add_f32_e32 v4, v4, v22
	v_fmac_f32_e32 v13, 0xba800000, v4
	v_fmac_f32_e32 v14, 0xba800000, v4
	v_fmac_f32_e32 v15, 0xba800000, v4
	v_fmac_f32_e32 v5, 0xba800000, v4
	v_fmac_f32_e32 v16, 0xba800000, v4
	v_fmac_f32_e32 v6, 0xba800000, v4
	v_fmac_f32_e32 v17, 0xba800000, v4
	v_fmac_f32_e32 v7, 0xba800000, v4
	v_fmac_f32_e32 v18, 0xba800000, v4
	v_fmac_f32_e32 v8, 0xba800000, v4
	v_fmac_f32_e32 v19, 0xba800000, v4
	v_fmac_f32_e32 v9, 0xba800000, v4
	v_fmac_f32_e32 v20, 0xba800000, v4
	v_fmac_f32_e32 v10, 0xba800000, v4
	v_fmac_f32_e32 v21, 0xba800000, v4
	v_fmac_f32_e32 v11, 0xba800000, v4
	v_mul_f32_e32 v23, v13, v13
	v_fmac_f32_e32 v23, v14, v14
	v_fmac_f32_e32 v23, v15, v15
	v_fmac_f32_e32 v23, v5, v5
	v_fmac_f32_e32 v23, v16, v16
	v_fmac_f32_e32 v23, v6, v6
	v_fmac_f32_e32 v23, v17, v17
	v_fmac_f32_e32 v23, v7, v7
	v_fmac_f32_e32 v23, v18, v18
	v_fmac_f32_e32 v23, v8, v8
	v_fmac_f32_e32 v23, v19, v19
	v_fmac_f32_e32 v23, v9, v9
	v_fmac_f32_e32 v23, v20, v20
	v_fmac_f32_e32 v23, v10, v10
	v_fmac_f32_e32 v23, v21, v21
	v_fmac_f32_e32 v23, v11, v11
	s_nop 1
	v_add_f32_dpp v23, v23, v23 row_ror:8 row_mask:0xf bank_mask:0xf bound_ctrl:1
	s_nop 1
	v_add_f32_dpp v23, v23, v23 row_ror:4 row_mask:0xf bank_mask:0xf bound_ctrl:1
	s_nop 1
	v_add_f32_dpp v23, v23, v23 row_ror:2 row_mask:0xf bank_mask:0xf bound_ctrl:1
	s_nop 1
	v_add_f32_dpp v23, v23, v23 row_ror:1 row_mask:0xf bank_mask:0xf bound_ctrl:1
	v_mov_b32_e32 v22, v23
	s_nop 1
	v_permlane16_swap_b32_e32 v23, v22
	v_add_f32_e32 v23, v23, v22
	v_mov_b32_e32 v22, v23
	s_nop 1
	v_permlane32_swap_b32_e32 v23, v22
	v_add_f32_e32 v23, v23, v22
	s_and_saveexec_b64 s[12:13], s[6:7]
	v_mov_b32_e32 v5, v23
	v_fmamk_f32 v5, v5, 0x3a800000, v112
	v_mul_f32_e32 v6, 0x4f800000, v5
	v_cmp_gt_f32_e32 vcc, s67, v5
	v_mul_f32_e32 v4, 0x3a800000, v4
	s_nop 0
	v_cndmask_b32_e32 v5, v5, v6, vcc
	v_sqrt_f32_e32 v6, v5
	s_nop 0
	v_add_u32_e32 v7, -1, v6
	v_fma_f32 v9, -v7, v6, v5
	v_add_u32_e32 v8, 1, v6
	v_cmp_ge_f32_e64 s[8:9], 0, v9
	s_nop 1
	v_cndmask_b32_e64 v7, v6, v7, s[8:9]
	v_fma_f32 v6, -v8, v6, v5
	v_cmp_lt_f32_e64 s[8:9], 0, v6
	s_nop 1
	v_cndmask_b32_e64 v6, v7, v8, s[8:9]
	v_mul_f32_e32 v7, 0x37800000, v6
	v_cndmask_b32_e32 v6, v6, v7, vcc
	v_cmp_class_f32_e32 vcc, v5, v113
	s_nop 1
	v_cndmask_b32_e32 v5, v6, v5, vcc
	v_div_scale_f32 v6, s[8:9], v5, v5, 1.0
	v_rcp_f32_e32 v7, v6
	s_nop 0
	v_fma_f32 v8, -v6, v7, 1.0
	v_fmac_f32_e32 v7, v8, v7
	v_div_scale_f32 v8, vcc, 1.0, v5, 1.0
	v_mul_f32_e32 v9, v8, v7
	v_fma_f32 v10, -v6, v9, v8
	v_fmac_f32_e32 v9, v10, v7
	v_fma_f32 v6, -v6, v9, v8
	s_nop 1
	v_div_fmas_f32 v6, v6, v7, v9
	v_div_fixup_f32 v5, v6, v5, 1.0
	ds_write_b64 v62, v[4:5] offset:120
	s_or_b64 exec, exec, s[12:13]
.Lgst_done:
.LBB0_742:
	v_lshlrev_b32_e32 v2, 4, v1
	v_and_b32_e32 v2, 0x1f0, v2
	v_add_u32_e32 v22, 0, v2
	v_lshrrev_b32_e32 v2, 1, v0
	s_ashr_i32 s6, s14, 1
	v_and_b32_e32 v23, 24, v2
	v_bfe_u32 v2, v1, 2, 2
	s_and_b32 s60, s6, 0xffffff80
	v_or_b32_e32 v19, v23, v2
	v_lshlrev_b32_e32 v2, 2, v1
	v_and_or_b32 v24, v2, 12, s60
	v_and_b32_e32 v20, 15, v1
	v_mul_u32_u24_e32 v19, 0x220, v19
	v_lshlrev_b32_e32 v24, 1, v24
	v_ashrrev_i32_e32 v21, 5, v1
	s_bfe_u32 s71, s14, 0x20006
	v_add3_u32 v122, 0, v19, v24
	v_and_b32_e32 v24, 31, v1
	v_lshlrev_b32_e32 v1, 8, v20
	v_lshl_or_b32 v1, s71, 13, v1
	v_and_or_b32 v70, v0, 48, v1
	v_add_u32_e32 v0, s3, v21
	v_ashrrev_i32_e32 v1, 31, v0
	v_lshlrev_b64 v[72:73], 12, v[0:1]
	v_add_u32_e32 v0, s40, v21
	v_ashrrev_i32_e32 v1, 31, v0
	v_lshlrev_b64 v[74:75], 12, v[0:1]
	v_add_u32_e32 v0, s41, v21
	v_ashrrev_i32_e32 v1, 31, v0
	v_lshlrev_b64 v[76:77], 12, v[0:1]
	v_add_u32_e32 v0, s62, v21
	v_ashrrev_i32_e32 v1, 31, v0
	v_lshlrev_b64 v[78:79], 12, v[0:1]
	v_add_u32_e32 v0, s63, v21
	v_ashrrev_i32_e32 v1, 31, v0
	v_lshlrev_b64 v[80:81], 12, v[0:1]
	v_add_u32_e32 v0, s64, v21
	v_ashrrev_i32_e32 v1, 31, v0
	s_lshl_b32 s72, s71, 5
	s_ashr_i32 s61, s60, 31
	v_lshlrev_b64 v[82:83], 12, v[0:1]
	v_add_u32_e32 v0, s65, v21
	v_or_b32_e32 v18, s72, v20
	s_cmp_lg_u32 s71, 0
	v_ashrrev_i32_e32 v1, 31, v0
	v_add_u32_e32 v25, 16, v21
	v_add_u32_e32 v26, 32, v21
	v_add_u32_e32 v27, 48, v21
	v_add_u32_e32 v28, 64, v21
	v_add_u32_e32 v29, 0x50, v21
	v_add_u32_e32 v30, 0x60, v21
	v_add_u32_e32 v31, 0x70, v21
	s_cselect_b64 s[54:55], -1, 0
	s_cmp_gt_u32 s71, 1
	v_or_b32_e32 v19, 16, v18
	v_lshlrev_b32_e32 v64, 2, v18
	v_lshlrev_b64 v[84:85], 12, v[0:1]
	v_add_u32_e32 v0, s66, v21
	v_cmp_gt_i32_e64 s[6:7], s24, v21
	v_cmp_gt_i32_e64 s[8:9], s24, v25
	v_cmp_gt_i32_e64 s[10:11], s24, v26
	v_cmp_gt_i32_e64 s[12:13], s24, v27
	v_cmp_gt_i32_e64 s[14:15], s24, v28
	v_cmp_gt_i32_e64 s[16:17], s24, v29
	v_cmp_gt_i32_e64 s[18:19], s24, v30
	v_cmp_gt_i32_e64 s[20:21], s24, v31
	s_cselect_b64 s[56:57], -1, 0
	s_cmp_eq_u32 s71, 3
	v_cmp_gt_u32_e64 s[22:23], s24, v18
	v_cmp_gt_u32_e64 s[24:25], s24, v19
	v_lshl_add_u64 v[18:19], s[26:27], 0, v[64:65]
	v_lshlrev_b32_e32 v64, 5, v24
	v_ashrrev_i32_e32 v1, 31, v0
	v_add_u32_e32 v2, s70, v21
	v_add_u32_e32 v4, s70, v25
	s_waitcnt lgkmcnt(0)
	v_add_u32_e32 v6, s70, v26
	v_add_u32_e32 v8, s70, v27
	v_add_u32_e32 v10, s70, v28
	v_add_u32_e32 v12, s70, v29
	v_add_u32_e32 v14, s70, v30
	v_add_u32_e32 v16, s70, v31
	s_cselect_b64 s[58:59], -1, 0
	v_lshlrev_b64 v[86:87], 12, v[0:1]
	v_lshl_add_u64 v[0:1], s[38:39], 0, v[64:65]
	s_add_i32 s70, s70, s72
	v_lshl_add_u64 v[88:89], v[0:1], 0, 16
	v_add_u32_e32 v0, s70, v20
	v_ashrrev_i32_e32 v1, 31, v0
	v_lshlrev_b64 v[0:1], 11, v[0:1]
	v_or_b32_e32 v0, v0, v23
	s_lshl_b64 s[26:27], s[60:61], 1
	v_lshl_add_u64 v[0:1], v[0:1], 0, s[26:27]
	v_lshl_add_u64 v[94:95], v[0:1], 0, s[46:47]
	v_add3_u32 v0, s70, 16, v20
	v_ashrrev_i32_e32 v1, 31, v0
	v_lshlrev_b64 v[0:1], 11, v[0:1]
	v_or_b32_e32 v0, v0, v23
	v_lshlrev_b32_e32 v32, 3, v21
	v_lshl_add_u64 v[0:1], v[0:1], 0, s[26:27]
	v_lshlrev_b32_e32 v25, 3, v25
	v_lshl_add_u64 v[108:109], v[0:1], 0, s[46:47]
	v_add_u32_e32 v0, 0, v32
	v_lshlrev_b32_e32 v26, 3, v26
	v_lshl_add_u64 v[66:67], v[18:19], 0, 64
	v_lshl_add_u64 v[18:19], s[36:37], 0, v[64:65]
	v_or_b32_e32 v72, v72, v64
	v_or_b32_e32 v74, v74, v64
	v_or_b32_e32 v76, v76, v64
	v_or_b32_e32 v78, v78, v64
	v_or_b32_e32 v80, v80, v64
	v_or_b32_e32 v82, v82, v64
	v_or_b32_e32 v84, v84, v64
	v_or_b32_e32 v86, v86, v64
	v_add_u32_e32 v64, 0x20000, v0
	v_add_u32_e32 v0, 0, v25
	v_lshlrev_b32_e32 v27, 3, v27
	v_add_u32_e32 v123, 0x20000, v0
	v_add_u32_e32 v0, 0, v26
	v_lshlrev_b32_e32 v28, 3, v28
	v_add_u32_e32 v124, 0x20000, v0
	v_add_u32_e32 v0, 0, v27
	v_lshlrev_b32_e32 v29, 3, v29
	v_add_u32_e32 v125, 0x20000, v0
	v_add_u32_e32 v0, 0, v28
	v_ashrrev_i32_e32 v3, 31, v2
	v_ashrrev_i32_e32 v5, 31, v4
	v_ashrrev_i32_e32 v7, 31, v6
	v_ashrrev_i32_e32 v9, 31, v8
	v_ashrrev_i32_e32 v11, 31, v10
	v_ashrrev_i32_e32 v13, 31, v12
	v_ashrrev_i32_e32 v15, 31, v14
	v_ashrrev_i32_e32 v17, 31, v16
	v_lshlrev_b32_e32 v30, 3, v30
	v_add_u32_e32 v126, 0x20000, v0
	v_add_u32_e32 v0, 0, v29
	v_lshlrev_b64 v[2:3], 11, v[2:3]
	v_lshlrev_b64 v[4:5], 11, v[4:5]
	v_lshlrev_b64 v[6:7], 11, v[6:7]
	v_lshlrev_b64 v[8:9], 11, v[8:9]
	v_lshlrev_b64 v[10:11], 11, v[10:11]
	v_lshlrev_b64 v[12:13], 11, v[12:13]
	v_lshlrev_b64 v[14:15], 11, v[14:15]
	v_lshlrev_b64 v[16:17], 11, v[16:17]
	v_lshlrev_b32_e32 v31, 3, v31
	v_lshl_add_u64 v[68:69], v[18:19], 0, 16
	v_lshlrev_b32_e32 v18, 4, v24
	v_add_u32_e32 v127, 0x20000, v0
	v_add_u32_e32 v0, 0, v30
	v_mul_lo_u32 v33, v21, s68
	v_or_b32_e32 v16, v16, v18
	v_or_b32_e32 v14, v14, v18
	v_or_b32_e32 v12, v12, v18
	v_or_b32_e32 v10, v10, v18
	v_or_b32_e32 v8, v8, v18
	v_or_b32_e32 v6, v6, v18
	v_or_b32_e32 v4, v4, v18
	v_or_b32_e32 v2, v2, v18
	v_add_u32_e32 v128, 0x20000, v0
	v_add_u32_e32 v0, 0, v31
	v_mov_b32_e32 v71, v65
	v_lshl_add_u64 v[90:91], v[16:17], 0, s[44:45]
	v_lshl_add_u64 v[92:93], v[14:15], 0, s[44:45]
	v_lshl_add_u64 v[96:97], v[12:13], 0, s[44:45]
	v_lshl_add_u64 v[98:99], v[10:11], 0, s[44:45]
	v_lshl_add_u64 v[100:101], v[8:9], 0, s[44:45]
	v_lshl_add_u64 v[102:103], v[6:7], 0, s[44:45]
	v_lshl_add_u64 v[104:105], v[4:5], 0, s[44:45]
	v_lshl_add_u64 v[106:107], v[2:3], 0, s[44:45]
	s_mov_b64 s[36:37], 0
	v_add_u32_e32 v129, 0x20000, v0
	v_add_u32_e32 v130, v22, v33
	s_barrier
	s_branch .LBB0_744

.LBB0_817:
	s_ashr_i32 s98, s40, 6
	s_min_u32 s99, s19, 0x1000
	s_add_i32 s99, s99, 31
	s_lshr_b32 s99, s99, 5
	s_sub_i32 s99, s99, s98
	s_cmp_lt_i32 s99, 1
	s_cbranch_scc1 .Lselpf_skip
	s_add_i32 s100, s99, 7
	s_lshr_b32 s101, s100, 29
	s_add_i32 s100, s100, s101
	s_ashr_i32 s100, s100, 3
	s_add_i32 s100, s100, -1
	s_lshl_b32 s100, s100, 3
	s_cmp_lt_u32 s99, 9
	s_cselect_b32 s101, s100, 8
	s_add_i32 s101, s101, s98
	s_cmp_lt_u32 s99, 17
	s_cselect_b32 s100, s100, 16
	s_add_i32 s100, s100, s98
	v_bfe_u32 v208, v106, 3, 3
	v_lshlrev_b32_e32 v209, 4, v106
	v_and_b32_e32 v209, 0x70, v209
	v_lshl_or_b32 v220, s98, 5, v208
	v_lshl_or_b32 v236, s101, 5, v208
	v_lshl_or_b32 v252, s100, 5, v208
	v_lshl_add_u32 v220, v220, 7, v209
	v_lshl_add_u32 v236, v236, 7, v209
	v_lshl_add_u32 v252, v252, 7, v209
	v_mov_b32_e32 v221, 0
	v_mov_b32_e32 v237, 0
	v_mov_b32_e32 v253, 0
	v_lshl_add_u64 v[220:221], s[6:7], 0, v[220:221]
	v_lshl_add_u64 v[236:237], s[6:7], 0, v[236:237]
	v_lshl_add_u64 v[252:253], s[6:7], 0, v[252:253]
	global_load_dwordx4 v[208:211], v[220:221], off
	global_load_dwordx4 v[212:215], v[220:221], off offset:1024
	global_load_dwordx4 v[216:219], v[220:221], off offset:2048
	global_load_dwordx4 v[220:223], v[220:221], off offset:3072
	global_load_dwordx4 v[224:227], v[236:237], off
	global_load_dwordx4 v[228:231], v[236:237], off offset:1024
	global_load_dwordx4 v[232:235], v[236:237], off offset:2048
	global_load_dwordx4 v[236:239], v[236:237], off offset:3072
	global_load_dwordx4 v[240:243], v[252:253], off
	global_load_dwordx4 v[244:247], v[252:253], off offset:1024
	global_load_dwordx4 v[248:251], v[252:253], off offset:2048
	global_load_dwordx4 v[252:255], v[252:253], off offset:3072
.Lselpf_skip:
	v_bfe_u32 v0, v106, 2, 2
	v_add_u32_e32 v16, s18, v0
	v_and_b32_e32 v96, 48, v106
	v_ashrrev_i32_e32 v17, 31, v16
	v_and_b32_e32 v4, 3, v106
	v_lshl_add_u64 v[18:19], s[14:15], 0, v[96:97]
	v_lshlrev_b64 v[0:1], 5, v[16:17]
	v_lshlrev_b64 v[2:3], 10, v[16:17]
	v_lshl_add_u64 v[0:1], s[16:17], 0, v[0:1]
	v_lshl_add_u64 v[8:9], v[18:19], 0, v[2:3]
	v_lshlrev_b32_e32 v20, 2, v4
	v_mov_b32_e32 v21, v97
	v_lshlrev_b32_e32 v22, 7, v4
	v_mov_b32_e32 v23, v97
	v_lshl_add_u64 v[10:11], v[0:1], 0, v[20:21]
	v_lshl_add_u64 v[4:5], v[8:9], 0, v[22:23]
	global_load_dword v30, v[10:11], off
	global_load_dwordx4 v[0:3], v[4:5], off
	s_nop 0
	global_load_dwordx4 v[4:7], v[4:5], off offset:64
	v_mov_b32_e32 v25, v97
	v_or_b32_e32 v24, 0x200, v22
	v_lshl_add_u64 v[12:13], v[8:9], 0, v[24:25]
	global_load_dword v31, v[10:11], off offset:16
	s_nop 0
	global_load_dwordx4 v[8:11], v[12:13], off
	s_nop 0
	global_load_dwordx4 v[12:15], v[12:13], off offset:64
	v_add_u32_e32 v16, 4, v16
	v_ashrrev_i32_e32 v17, 31, v16
	v_lshlrev_b64 v[26:27], 5, v[16:17]
	v_lshlrev_b64 v[16:17], 10, v[16:17]
	v_lshl_add_u64 v[26:27], s[16:17], 0, v[26:27]
	v_lshl_add_u64 v[28:29], v[18:19], 0, v[16:17]
	v_lshl_add_u64 v[26:27], v[26:27], 0, v[20:21]
	v_lshl_add_u64 v[20:21], v[28:29], 0, v[22:23]
	global_load_dword v57, v[26:27], off
	global_load_dwordx4 v[16:19], v[20:21], off
	v_lshl_add_u64 v[28:29], v[28:29], 0, v[24:25]
	global_load_dwordx4 v[20:23], v[20:21], off offset:64
	s_nop 0
	global_load_dword v59, v[26:27], off offset:16
	s_nop 0
	global_load_dwordx4 v[24:27], v[28:29], off
	v_bfe_u32 v58, v106, 4, 2
	s_ashr_i32 s12, s40, 6
	s_mul_i32 s8, s12, 0x900
	v_mov_b32_e32 v99, v97
	s_add_i32 s8, s8, 0
	s_add_i32 s8, s8, 0x22000
	v_and_b32_e32 v56, 15, v106
	v_bfe_u32 v191, v106, 3, 3
	s_waitcnt vmcnt(10)
	v_and_b32_e32 v30, 0x7fffffff, v30
	s_waitcnt vmcnt(9)
	v_lshlrev_b32_e32 v32, 16, v0
	v_and_b32_e32 v33, 0xffff0000, v0
	v_lshlrev_b32_e32 v0, 16, v1
	v_and_b32_e32 v1, 0xffff0000, v1
	v_lshlrev_b32_e32 v34, 16, v2
	v_and_b32_e32 v35, 0xffff0000, v2
	v_lshlrev_b32_e32 v2, 16, v3
	v_and_b32_e32 v3, 0xffff0000, v3
	s_waitcnt vmcnt(8)
	v_lshlrev_b32_e32 v36, 16, v4
	v_and_b32_e32 v37, 0xffff0000, v4
	v_lshlrev_b32_e32 v4, 16, v5
	v_and_b32_e32 v5, 0xffff0000, v5
	v_lshlrev_b32_e32 v38, 16, v6
	v_and_b32_e32 v39, 0xffff0000, v6
	v_lshlrev_b32_e32 v6, 16, v7
	v_and_b32_e32 v7, 0xffff0000, v7
	s_waitcnt vmcnt(7)
	v_and_b32_e32 v40, 0x7fffffff, v31
	s_waitcnt vmcnt(6)
	v_lshlrev_b32_e32 v46, 16, v11
	v_pk_mul_f32 v[32:33], v[30:31], v[32:33] op_sel_hi:[0,1]
	v_pk_mul_f32 v[48:49], v[30:31], v[0:1] op_sel_hi:[0,1]
	v_pk_mul_f32 v[34:35], v[30:31], v[34:35] op_sel_hi:[0,1]
	v_pk_mul_f32 v[50:51], v[30:31], v[2:3] op_sel_hi:[0,1]
	v_pk_mul_f32 v[36:37], v[30:31], v[36:37] op_sel_hi:[0,1]
	v_pk_mul_f32 v[52:53], v[30:31], v[4:5] op_sel_hi:[0,1]
	v_pk_mul_f32 v[38:39], v[30:31], v[38:39] op_sel_hi:[0,1]
	v_pk_mul_f32 v[30:31], v[30:31], v[6:7] op_sel_hi:[0,1]
	v_and_b32_e32 v47, 0xffff0000, v11
	v_cvt_pk_bf16_f32 v0, v32, v33
	v_cvt_pk_bf16_f32 v7, v30, v31
	v_pk_mul_f32 v[32:33], v[40:41], v[46:47] op_sel_hi:[0,1]
	global_load_dwordx4 v[28:31], v[28:29], off offset:64
	v_lshlrev_b32_e32 v44, 16, v10
	v_and_b32_e32 v45, 0xffff0000, v10
	v_cvt_pk_bf16_f32 v11, v32, v33
	s_waitcnt vmcnt(6)
	v_lshlrev_b32_e32 v32, 16, v12
	v_and_b32_e32 v33, 0xffff0000, v12
	v_pk_mul_f32 v[44:45], v[40:41], v[44:45] op_sel_hi:[0,1]
	v_pk_mul_f32 v[32:33], v[40:41], v[32:33] op_sel_hi:[0,1]
	v_cvt_pk_bf16_f32 v10, v44, v45
	v_cvt_pk_bf16_f32 v12, v32, v33
	v_lshlrev_b32_e32 v32, 16, v13
	v_and_b32_e32 v33, 0xffff0000, v13
	v_add_u32_e32 v44, s18, v58
	v_pk_mul_f32 v[32:33], v[40:41], v[32:33] op_sel_hi:[0,1]
	v_ashrrev_i32_e32 v45, 31, v44
	v_lshlrev_b32_e32 v42, 16, v8
	v_and_b32_e32 v43, 0xffff0000, v8
	v_cvt_pk_bf16_f32 v13, v32, v33
	v_lshlrev_b64 v[32:33], 5, v[44:45]
	v_lshlrev_b32_e32 v8, 16, v9
	v_and_b32_e32 v9, 0xffff0000, v9
	v_pk_mul_f32 v[42:43], v[40:41], v[42:43] op_sel_hi:[0,1]
	v_cvt_pk_bf16_f32 v4, v36, v37
	v_lshl_add_u64 v[36:37], s[16:17], 0, v[32:33]
	v_pk_mul_f32 v[54:55], v[40:41], v[8:9] op_sel_hi:[0,1]
	v_cvt_pk_bf16_f32 v2, v34, v35
	v_cvt_pk_bf16_f32 v6, v38, v39
	v_cvt_pk_bf16_f32 v8, v42, v43
	v_lshlrev_b32_e32 v42, 16, v14
	global_load_dwordx4 v[32:35], v[36:37], off offset:16
	s_nop 0
	global_load_dwordx4 v[36:39], v[36:37], off
	v_and_b32_e32 v43, 0xffff0000, v14
	v_pk_mul_f32 v[42:43], v[40:41], v[42:43] op_sel_hi:[0,1]
	v_cvt_pk_bf16_f32 v14, v42, v43
	v_lshlrev_b32_e32 v42, 16, v15
	v_and_b32_e32 v43, 0xffff0000, v15
	v_pk_mul_f32 v[40:41], v[40:41], v[42:43] op_sel_hi:[0,1]
	v_cvt_pk_bf16_f32 v1, v48, v49
	v_cvt_pk_bf16_f32 v15, v40, v41
	s_waitcnt vmcnt(7)
	v_and_b32_e32 v48, 0x7fffffff, v57
	s_waitcnt vmcnt(6)
	v_lshlrev_b32_e32 v40, 16, v16
	v_and_b32_e32 v41, 0xffff0000, v16
	v_pk_mul_f32 v[40:41], v[48:49], v[40:41] op_sel_hi:[0,1]
	v_cvt_pk_bf16_f32 v16, v40, v41
	v_lshlrev_b32_e32 v40, 16, v17
	v_and_b32_e32 v41, 0xffff0000, v17
	v_pk_mul_f32 v[40:41], v[48:49], v[40:41] op_sel_hi:[0,1]
	v_cvt_pk_bf16_f32 v17, v40, v41
	v_lshlrev_b32_e32 v40, 16, v18
	v_and_b32_e32 v41, 0xffff0000, v18
	v_pk_mul_f32 v[40:41], v[48:49], v[40:41] op_sel_hi:[0,1]
	v_cvt_pk_bf16_f32 v18, v40, v41
	v_lshlrev_b32_e32 v40, 16, v19
	v_and_b32_e32 v41, 0xffff0000, v19
	v_pk_mul_f32 v[40:41], v[48:49], v[40:41] op_sel_hi:[0,1]
	v_cvt_pk_bf16_f32 v19, v40, v41
	v_add_u32_e32 v40, 4, v44
	v_ashrrev_i32_e32 v41, 31, v40
	v_lshlrev_b64 v[40:41], 5, v[40:41]
	v_lshl_add_u64 v[44:45], s[16:17], 0, v[40:41]
	global_load_dwordx4 v[40:43], v[44:45], off offset:16
	s_nop 0
	global_load_dwordx4 v[44:47], v[44:45], off
	v_cvt_pk_bf16_f32 v3, v50, v51
	s_waitcnt vmcnt(7)
	v_lshlrev_b32_e32 v50, 16, v20
	v_and_b32_e32 v51, 0xffff0000, v20
	v_pk_mul_f32 v[50:51], v[48:49], v[50:51] op_sel_hi:[0,1]
	v_cvt_pk_bf16_f32 v20, v50, v51
	v_lshlrev_b32_e32 v50, 16, v21
	v_and_b32_e32 v51, 0xffff0000, v21
	v_pk_mul_f32 v[50:51], v[48:49], v[50:51] op_sel_hi:[0,1]
	v_cvt_pk_bf16_f32 v21, v50, v51
	v_lshlrev_b32_e32 v50, 16, v22
	v_and_b32_e32 v51, 0xffff0000, v22
	v_pk_mul_f32 v[50:51], v[48:49], v[50:51] op_sel_hi:[0,1]
	v_cvt_pk_bf16_f32 v22, v50, v51
	v_lshlrev_b32_e32 v50, 16, v23
	v_and_b32_e32 v51, 0xffff0000, v23
	v_pk_mul_f32 v[48:49], v[48:49], v[50:51] op_sel_hi:[0,1]
	v_cvt_pk_bf16_f32 v23, v48, v49
	s_waitcnt vmcnt(6)
	v_and_b32_e32 v48, 0x7fffffff, v59
	s_waitcnt vmcnt(5)
	v_lshlrev_b32_e32 v50, 16, v24
	v_and_b32_e32 v51, 0xffff0000, v24
	v_pk_mul_f32 v[50:51], v[48:49], v[50:51] op_sel_hi:[0,1]
	v_cvt_pk_bf16_f32 v24, v50, v51
	v_lshlrev_b32_e32 v50, 16, v25
	v_and_b32_e32 v51, 0xffff0000, v25
	v_pk_mul_f32 v[50:51], v[48:49], v[50:51] op_sel_hi:[0,1]
	v_cvt_pk_bf16_f32 v25, v50, v51
	v_lshlrev_b32_e32 v50, 16, v26
	v_and_b32_e32 v51, 0xffff0000, v26
	v_pk_mul_f32 v[50:51], v[48:49], v[50:51] op_sel_hi:[0,1]
	v_cvt_pk_bf16_f32 v26, v50, v51
	v_lshlrev_b32_e32 v50, 16, v27
	v_and_b32_e32 v51, 0xffff0000, v27
	v_pk_mul_f32 v[50:51], v[48:49], v[50:51] op_sel_hi:[0,1]
	v_cvt_pk_bf16_f32 v27, v50, v51
	s_waitcnt vmcnt(4)
	v_lshlrev_b32_e32 v50, 16, v28
	v_and_b32_e32 v51, 0xffff0000, v28
	v_pk_mul_f32 v[50:51], v[48:49], v[50:51] op_sel_hi:[0,1]
	v_cvt_pk_bf16_f32 v28, v50, v51
	v_lshlrev_b32_e32 v50, 16, v29
	v_and_b32_e32 v51, 0xffff0000, v29
	v_pk_mul_f32 v[50:51], v[48:49], v[50:51] op_sel_hi:[0,1]
	v_cvt_pk_bf16_f32 v29, v50, v51
	v_lshlrev_b32_e32 v50, 16, v30
	v_and_b32_e32 v51, 0xffff0000, v30
	v_pk_mul_f32 v[50:51], v[48:49], v[50:51] op_sel_hi:[0,1]
	v_cvt_pk_bf16_f32 v30, v50, v51
	v_lshlrev_b32_e32 v50, 16, v31
	v_and_b32_e32 v51, 0xffff0000, v31
	v_pk_mul_f32 v[48:49], v[48:49], v[50:51] op_sel_hi:[0,1]
	s_waitcnt vmcnt(2)
	v_cmp_gt_f32_e32 vcc, 0, v36
	v_cvt_pk_bf16_f32 v31, v48, v49
	v_cvt_pk_bf16_f32 v5, v52, v53
	v_cndmask_b32_e64 v48, 0, -1.0, vcc
	v_cmp_nlt_f32_e32 vcc, 0, v36
	v_cvt_pk_bf16_f32 v9, v54, v55
	s_nop 0
	v_cndmask_b32_e32 v162, 1.0, v48, vcc
	v_cmp_gt_f32_e32 vcc, 0, v37
	s_nop 1
	v_cndmask_b32_e64 v36, 0, -1.0, vcc
	v_cmp_nlt_f32_e32 vcc, 0, v37
	s_nop 1
	v_cndmask_b32_e32 v163, 1.0, v36, vcc
	v_cmp_gt_f32_e32 vcc, 0, v38
	s_nop 1
	v_cndmask_b32_e64 v36, 0, -1.0, vcc
	v_cmp_nlt_f32_e32 vcc, 0, v38
	s_nop 1
	v_cndmask_b32_e32 v164, 1.0, v36, vcc
	v_cmp_gt_f32_e32 vcc, 0, v39
	s_nop 1
	v_cndmask_b32_e64 v36, 0, -1.0, vcc
	v_cmp_nlt_f32_e32 vcc, 0, v39
	s_nop 1
	v_cndmask_b32_e32 v165, 1.0, v36, vcc
	v_cmp_gt_f32_e32 vcc, 0, v32
	s_nop 1
	v_cndmask_b32_e64 v36, 0, -1.0, vcc
	v_cmp_nlt_f32_e32 vcc, 0, v32
	s_nop 1
	v_cndmask_b32_e32 v166, 1.0, v36, vcc
	v_cmp_gt_f32_e32 vcc, 0, v33
	s_nop 1
	v_cndmask_b32_e64 v32, 0, -1.0, vcc
	v_cmp_nlt_f32_e32 vcc, 0, v33
	v_lshlrev_b32_e32 v33, 2, v56
	s_nop 0
	v_cndmask_b32_e32 v167, 1.0, v32, vcc
	v_cmp_gt_f32_e32 vcc, 0, v34
	s_nop 1
	v_cndmask_b32_e64 v32, 0, -1.0, vcc
	v_cmp_nlt_f32_e32 vcc, 0, v34
	s_nop 1
	v_cndmask_b32_e32 v168, 1.0, v32, vcc
	v_cmp_gt_f32_e32 vcc, 0, v35
	s_nop 1
	v_cndmask_b32_e64 v32, 0, -1.0, vcc
	v_cmp_nlt_f32_e32 vcc, 0, v35
	s_nop 1
	v_cndmask_b32_e32 v169, 1.0, v32, vcc
	s_waitcnt vmcnt(0)
	v_cmp_gt_f32_e32 vcc, 0, v44
	s_nop 1
	v_cndmask_b32_e64 v32, 0, -1.0, vcc
	v_cmp_nlt_f32_e32 vcc, 0, v44
	s_nop 1
	v_cndmask_b32_e32 v170, 1.0, v32, vcc
	v_cmp_gt_f32_e32 vcc, 0, v45
	s_nop 1
	v_cndmask_b32_e64 v32, 0, -1.0, vcc
	v_cmp_nlt_f32_e32 vcc, 0, v45
	s_nop 1
	v_cndmask_b32_e32 v171, 1.0, v32, vcc
	v_cmp_gt_f32_e32 vcc, 0, v46
	s_nop 1
	v_cndmask_b32_e64 v32, 0, -1.0, vcc
	v_cmp_nlt_f32_e32 vcc, 0, v46
	s_nop 1
	v_cndmask_b32_e32 v172, 1.0, v32, vcc
	v_cmp_gt_f32_e32 vcc, 0, v47
	s_nop 1
	v_cndmask_b32_e64 v32, 0, -1.0, vcc
	v_cmp_nlt_f32_e32 vcc, 0, v47
	s_nop 1
	v_cndmask_b32_e32 v173, 1.0, v32, vcc
	v_cmp_gt_f32_e32 vcc, 0, v40
	s_nop 1
	v_cndmask_b32_e64 v32, 0, -1.0, vcc
	v_cmp_nlt_f32_e32 vcc, 0, v40
	s_nop 1
	v_cndmask_b32_e32 v174, 1.0, v32, vcc
	v_cmp_gt_f32_e32 vcc, 0, v41
	s_nop 1
	v_cndmask_b32_e64 v32, 0, -1.0, vcc
	v_cmp_nlt_f32_e32 vcc, 0, v41
	s_nop 1
	v_cndmask_b32_e32 v175, 1.0, v32, vcc
	v_cmp_gt_f32_e32 vcc, 0, v42
	s_nop 1
	v_cndmask_b32_e64 v32, 0, -1.0, vcc
	v_cmp_nlt_f32_e32 vcc, 0, v42
	s_nop 1
	v_cndmask_b32_e32 v176, 1.0, v32, vcc
	v_cmp_gt_f32_e32 vcc, 0, v43
	s_nop 1
	v_cndmask_b32_e64 v32, 0, -1.0, vcc
	v_cmp_nlt_f32_e32 vcc, 0, v43
	s_nop 1
	v_cndmask_b32_e32 v177, 1.0, v32, vcc
	v_lshlrev_b32_e32 v32, 4, v106
	v_and_b32_e32 v98, 0x70, v32
	v_lshl_add_u64 v[100:101], s[6:7], 0, v[98:99]
	s_min_u32 s7, s19, 0x1000
	s_add_i32 s7, s7, 31
	v_mov_b32_e32 v32, s8
	s_lshl_b32 s6, s12, 7
	s_lshr_b32 s7, s7, 5
	v_mad_u32_u24 v178, v191, s26, v32
	v_mad_u32_u24 v179, v56, s26, v32
	v_lshlrev_b32_e32 v32, 14, v58
	s_add_i32 s6, s6, 0
	s_sub_i32 s8, s7, s12
	s_cmp_lt_i32 s8, 1
	v_add3_u32 v180, s6, v32, v33
	s_cbranch_scc1 .LBB0_826
	s_add_i32 s6, s8, 7
	s_lshr_b32 s7, s6, 29
	s_add_i32 s6, s6, s7
	s_ashr_i32 s6, s6, 3
	s_add_i32 s7, s6, -1
	s_lshl_b32 s9, s7, 3
	s_cmp_lt_u32 s8, 9
	s_cselect_b32 s40, s9, 8
	s_add_i32 s40, s40, s12
	s_cmp_lt_u32 s8, 17
	s_cselect_b32 s8, s9, 16
	s_add_i32 s8, s8, s12
	v_lshl_or_b32 v102, s12, 5, v191
	v_lshl_or_b32 v40, s40, 5, v191
	v_lshl_or_b32 v48, s8, 5, v191
	v_ashrrev_i32_e32 v103, 31, v102
	v_ashrrev_i32_e32 v41, 31, v40
	v_ashrrev_i32_e32 v49, 31, v48
	v_lshlrev_b64 v[32:33], 7, v[102:103]
	v_lshlrev_b64 v[40:41], 7, v[40:41]
	v_lshlrev_b64 v[48:49], 7, v[48:49]
	v_lshl_add_u64 v[36:37], v[100:101], 0, v[32:33]
	v_lshl_add_u64 v[44:45], v[100:101], 0, v[40:41]
	v_lshl_add_u64 v[52:53], v[100:101], 0, v[48:49]
	s_waitcnt vmcnt(0)
	v_mov_b32_e32 v64, v208
	v_mov_b32_e32 v65, v209
	v_mov_b32_e32 v66, v210
	v_mov_b32_e32 v67, v211
	v_mov_b32_e32 v68, v212
	v_mov_b32_e32 v69, v213
	v_mov_b32_e32 v70, v214
	v_mov_b32_e32 v71, v215
	v_mov_b32_e32 v32, v216
	v_mov_b32_e32 v33, v217
	v_mov_b32_e32 v34, v218
	v_mov_b32_e32 v35, v219
	v_mov_b32_e32 v36, v220
	v_mov_b32_e32 v37, v221
	v_mov_b32_e32 v38, v222
	v_mov_b32_e32 v39, v223
	v_mov_b32_e32 v72, v224
	v_mov_b32_e32 v73, v225
	v_mov_b32_e32 v74, v226
	v_mov_b32_e32 v75, v227
	v_mov_b32_e32 v76, v228
	v_mov_b32_e32 v77, v229
	v_mov_b32_e32 v78, v230
	v_mov_b32_e32 v79, v231
	v_mov_b32_e32 v40, v232
	v_mov_b32_e32 v41, v233
	v_mov_b32_e32 v42, v234
	v_mov_b32_e32 v43, v235
	v_mov_b32_e32 v44, v236
	v_mov_b32_e32 v45, v237
	v_mov_b32_e32 v46, v238
	v_mov_b32_e32 v47, v239
	v_mov_b32_e32 v80, v240
	v_mov_b32_e32 v81, v241
	v_mov_b32_e32 v82, v242
	v_mov_b32_e32 v83, v243
	v_mov_b32_e32 v84, v244
	v_mov_b32_e32 v85, v245
	v_mov_b32_e32 v86, v246
	v_mov_b32_e32 v87, v247
	v_mov_b32_e32 v48, v248
	v_mov_b32_e32 v49, v249
	v_mov_b32_e32 v50, v250
	v_mov_b32_e32 v51, v251
	v_mov_b32_e32 v52, v252
	v_mov_b32_e32 v53, v253
	v_mov_b32_e32 v54, v254
	v_mov_b32_e32 v55, v255
	s_and_saveexec_b64 s[98:99], s[28:29]
	s_cbranch_execz .Lselq_skip
	v_mov_b32_e32 v240, 1
	global_atomic_add v240, v97, v240, s[10:11] sc0

	.amdhsa_kernel _Z14fwd_megakernel4Args
		.amdhsa_group_segment_fixed_size 0
		.amdhsa_private_segment_fixed_size 0
		.amdhsa_kernarg_size 480
		.amdhsa_user_sgpr_count 2
		.amdhsa_user_sgpr_dispatch_ptr 0
		.amdhsa_user_sgpr_queue_ptr 0
		.amdhsa_user_sgpr_kernarg_segment_ptr 1
		.amdhsa_user_sgpr_dispatch_id 0
		.amdhsa_user_sgpr_kernarg_preload_length 0
		.amdhsa_user_sgpr_kernarg_preload_offset 0
		.amdhsa_user_sgpr_private_segment_size 0
		.amdhsa_uses_dynamic_stack 0
		.amdhsa_enable_private_segment 0
		.amdhsa_system_sgpr_workgroup_id_x 1
		.amdhsa_system_sgpr_workgroup_id_y 0
		.amdhsa_system_sgpr_workgroup_id_z 0
		.amdhsa_system_sgpr_workgroup_info 0
		.amdhsa_system_vgpr_workitem_id 2
		.amdhsa_next_free_vgpr 256
		.amdhsa_next_free_sgpr 102
		.amdhsa_accum_offset 256
		.amdhsa_reserve_vcc 1
		.amdhsa_float_round_mode_32 0
		.amdhsa_float_round_mode_16_64 0
		.amdhsa_float_denorm_mode_32 3
		.amdhsa_float_denorm_mode_16_64 3
		.amdhsa_dx10_clamp 1
		.amdhsa_ieee_mode 1
		.amdhsa_fp16_overflow 0
		.amdhsa_tg_split 0
		.amdhsa_exception_fp_ieee_invalid_op 0
		.amdhsa_exception_fp_denorm_src 0
		.amdhsa_exception_fp_ieee_div_zero 0
		.amdhsa_exception_fp_ieee_overflow 0
		.amdhsa_exception_fp_ieee_underflow 0
		.amdhsa_exception_fp_ieee_inexact 0
		.amdhsa_exception_int_div_zero 0
	.end_amdhsa_kernel

amdhsa.kernels:
  - .agpr_count:     0
    .args:
      - .offset:         0
        .size:           224
        .value_kind:     by_value
      - .offset:         224
        .size:           4
        .value_kind:     hidden_block_count_x
      - .offset:         228
        .size:           4
        .value_kind:     hidden_block_count_y
      - .offset:         232
        .size:           4
        .value_kind:     hidden_block_count_z
      - .offset:         236
        .size:           2
        .value_kind:     hidden_group_size_x
      - .offset:         238
        .size:           2
        .value_kind:     hidden_group_size_y
      - .offset:         240
        .size:           2
        .value_kind:     hidden_group_size_z
      - .offset:         242
        .size:           2
        .value_kind:     hidden_remainder_x
      - .offset:         244
        .size:           2
        .value_kind:     hidden_remainder_y
      - .offset:         246
        .size:           2
        .value_kind:     hidden_remainder_z
      - .offset:         264
        .size:           8
        .value_kind:     hidden_global_offset_x
      - .offset:         272
        .size:           8
        .value_kind:     hidden_global_offset_y
      - .offset:         280
        .size:           8
        .value_kind:     hidden_global_offset_z
      - .offset:         288
        .size:           2
        .value_kind:     hidden_grid_dims
      - .offset:         312
        .size:           8
        .value_kind:     hidden_multigrid_sync_arg
      - .offset:         344
        .size:           4
        .value_kind:     hidden_dynamic_lds_size
    .group_segment_fixed_size: 0
    .kernarg_segment_align: 8
    .kernarg_segment_size: 480
    .language:       OpenCL C
    .language_version:
      - 2
      - 0
    .max_flat_workgroup_size: 512
    .name:           _Z14fwd_megakernel4Args
    .private_segment_fixed_size: 0
    .sgpr_count:     108
    .sgpr_spill_count: 4
    .symbol:         _Z14fwd_megakernel4Args.kd
    .uniform_work_group_size: 1
    .uses_dynamic_stack: false
    .vgpr_count:     256
    .vgpr_spill_count: 0
    .wavefront_size: 64
